# GEMM epilogues no longer aligned between the two wave halves (two barriers per unit dropped), on top of aligned K-loops + MMA-path cleanup
# baseline (speedup 1.0000x reference)
.LBB0_269:
	v_lshl_add_u32 v142, s50, 8, v1
	v_lshl_or_b32 v144, s72, 8, v254
	v_ashrrev_i32_e32 v143, 31, v142
	v_ashrrev_i32_e32 v145, 31, v144
	v_lshlrev_b64 v[146:147], 15, v[142:143]
	v_lshl_add_u64 v[146:147], s[10:11], 0, v[146:147]
	v_lshlrev_b64 v[144:145], 1, v[144:145]
	v_lshl_add_u64 v[146:147], v[146:147], 0, v[144:145]
	v_cvt_pk_bf16_f32 v122, v122, v123
	v_cvt_pk_bf16_f32 v123, v124, v125
	v_cvt_pk_bf16_f32 v124, v114, v115
	v_cvt_pk_bf16_f32 v125, v116, v117
	global_store_dwordx4 v[146:147], v[122:125], off
	v_cvt_pk_bf16_f32 v114, v126, v127
	v_cvt_pk_bf16_f32 v115, v128, v129
	v_cvt_pk_bf16_f32 v116, v118, v119
	v_cvt_pk_bf16_f32 v117, v120, v121
	global_store_dwordx4 v[146:147], v[114:117], off offset:256
	v_cvt_pk_bf16_f32 v106, v106, v107
	v_cvt_pk_bf16_f32 v107, v108, v109
	v_cvt_pk_bf16_f32 v108, v98, v99
	v_cvt_pk_bf16_f32 v109, v100, v101
	s_nop 1
	v_or_b32_e32 v114, 16, v142
	v_ashrrev_i32_e32 v115, 31, v114
	v_lshlrev_b64 v[114:115], 15, v[114:115]
	v_lshl_add_u64 v[114:115], s[10:11], 0, v[114:115]
	v_lshl_add_u64 v[114:115], v[114:115], 0, v[144:145]
	global_store_dwordx4 v[114:115], v[106:109], off
	v_cvt_pk_bf16_f32 v98, v110, v111
	v_cvt_pk_bf16_f32 v99, v112, v113
	v_cvt_pk_bf16_f32 v100, v102, v103
	v_cvt_pk_bf16_f32 v101, v104, v105
	global_store_dwordx4 v[114:115], v[98:101], off offset:256
	v_cvt_pk_bf16_f32 v90, v90, v91
	v_cvt_pk_bf16_f32 v91, v92, v93
	v_cvt_pk_bf16_f32 v92, v82, v83
	v_cvt_pk_bf16_f32 v93, v84, v85
	s_nop 1
	v_or_b32_e32 v98, 32, v142
	v_ashrrev_i32_e32 v99, 31, v98
	v_lshlrev_b64 v[98:99], 15, v[98:99]
	v_lshl_add_u64 v[98:99], s[10:11], 0, v[98:99]
	v_lshl_add_u64 v[98:99], v[98:99], 0, v[144:145]
	global_store_dwordx4 v[98:99], v[90:93], off
	v_cvt_pk_bf16_f32 v82, v94, v95
	v_cvt_pk_bf16_f32 v83, v96, v97
	v_cvt_pk_bf16_f32 v84, v86, v87
	v_cvt_pk_bf16_f32 v85, v88, v89
	global_store_dwordx4 v[98:99], v[82:85], off offset:256
	v_cvt_pk_bf16_f32 v58, v58, v59
	v_cvt_pk_bf16_f32 v59, v60, v61
	v_cvt_pk_bf16_f32 v60, v50, v51
	v_cvt_pk_bf16_f32 v61, v52, v53
	s_nop 1
	v_or_b32_e32 v82, 48, v142
	v_ashrrev_i32_e32 v83, 31, v82
	v_lshlrev_b64 v[82:83], 15, v[82:83]
	v_lshl_add_u64 v[82:83], s[10:11], 0, v[82:83]
	v_lshl_add_u64 v[82:83], v[82:83], 0, v[144:145]
	global_store_dwordx4 v[82:83], v[58:61], off
	v_cvt_pk_bf16_f32 v50, v62, v63
	v_cvt_pk_bf16_f32 v51, v64, v65
	v_cvt_pk_bf16_f32 v52, v54, v55
	v_cvt_pk_bf16_f32 v53, v56, v57
	v_add_co_u32_e32 v56, vcc, s68, v146
	global_store_dwordx4 v[82:83], v[50:53], off offset:256
	v_lshl_add_u64 v[54:55], v[146:147], 0, s[34:35]
	v_addc_co_u32_e32 v57, vcc, 0, v147, vcc
	v_cvt_pk_bf16_f32 v50, v78, v79
	v_cvt_pk_bf16_f32 v51, v80, v81
	v_cvt_pk_bf16_f32 v52, v70, v71
	v_cvt_pk_bf16_f32 v53, v72, v73
	global_store_dwordx4 v[56:57], v[50:53], off
	s_nop 1
	v_cvt_pk_bf16_f32 v50, v74, v75
	v_cvt_pk_bf16_f32 v51, v76, v77
	v_cvt_pk_bf16_f32 v52, v66, v67
	v_cvt_pk_bf16_f32 v53, v68, v69
	global_store_dwordx4 v[54:55], v[50:53], off offset:256
	v_cvt_pk_bf16_f32 v46, v46, v47
	v_cvt_pk_bf16_f32 v47, v48, v49
	v_cvt_pk_bf16_f32 v48, v38, v39
	v_add_co_u32_e32 v38, vcc, s69, v146
	s_nop 0
	v_lshl_add_u64 v[50:51], v[146:147], 0, s[36:37]
	v_addc_co_u32_e32 v39, vcc, 0, v147, vcc
	v_cvt_pk_bf16_f32 v49, v40, v41
	global_store_dwordx4 v[38:39], v[46:49], off
	v_cvt_pk_bf16_f32 v38, v42, v43
	v_cvt_pk_bf16_f32 v39, v44, v45
	v_cvt_pk_bf16_f32 v40, v34, v35
	v_cvt_pk_bf16_f32 v41, v36, v37
	global_store_dwordx4 v[50:51], v[38:41], off offset:256
	v_cvt_pk_bf16_f32 v30, v30, v31
	v_cvt_pk_bf16_f32 v31, v32, v33
	v_cvt_pk_bf16_f32 v32, v22, v23
	v_add_co_u32_e32 v22, vcc, s70, v146
	v_lshl_add_u64 v[34:35], v[146:147], 0, s[38:39]
	s_nop 0
	v_addc_co_u32_e32 v23, vcc, 0, v147, vcc
	v_cvt_pk_bf16_f32 v33, v24, v25
	global_store_dwordx4 v[22:23], v[30:33], off
	v_cvt_pk_bf16_f32 v22, v26, v27
	v_cvt_pk_bf16_f32 v23, v28, v29
	v_cvt_pk_bf16_f32 v24, v18, v19
	v_cvt_pk_bf16_f32 v25, v20, v21
	global_store_dwordx4 v[34:35], v[22:25], off offset:256
	v_cvt_pk_bf16_f32 v14, v14, v15
	v_cvt_pk_bf16_f32 v15, v16, v17
	v_cvt_pk_bf16_f32 v16, v6, v7
	v_add_co_u32_e32 v6, vcc, s71, v146
	v_lshl_add_u64 v[18:19], v[146:147], 0, s[40:41]
	s_nop 0
	v_addc_co_u32_e32 v7, vcc, 0, v147, vcc
	s_andn2_b64 vcc, exec, s[4:5]
	s_mov_b64 s[4:5], -1
	v_cvt_pk_bf16_f32 v17, v8, v9
	global_store_dwordx4 v[6:7], v[14:17], off
	v_cvt_pk_bf16_f32 v6, v10, v11
	v_cvt_pk_bf16_f32 v7, v12, v13
	v_cvt_pk_bf16_f32 v8, v2, v3
	v_cvt_pk_bf16_f32 v9, v4, v5
	global_store_dwordx4 v[18:19], v[6:9], off offset:256
	s_cbranch_vccnz .LBB0_258
	s_andn2_b64 vcc, exec, s[6:7]
	s_cbranch_vccnz .LBB0_257
	s_branch .LBB0_257
.LBB0_272:
	s_waitcnt vmcnt(0)
	v_readlane_b32 s80, v255, 5
	s_cmp_lg_u64 s[14:15], 0
	s_cbranch_scc0 .Lmy_na_0
	s_barrier
.Lmy_na_0:
	s_barrier

.LBB0_285:
	v_lshl_add_u32 v8, s54, 8, v1
	v_lshl_or_b32 v2, s72, 8, v187
	v_ashrrev_i32_e32 v9, 31, v8
	v_ashrrev_i32_e32 v3, 31, v2
	v_lshlrev_b64 v[4:5], 15, v[8:9]
	v_lshl_add_u64 v[4:5], s[12:13], 0, v[4:5]
	v_lshlrev_b64 v[10:11], 1, v[2:3]
	v_lshl_add_u64 v[2:3], v[4:5], 0, v[10:11]
	v_pk_mul_f32 v[4:5], v[158:159], s[36:37] op_sel_hi:[1,0]
	v_pk_mul_f32 v[6:7], v[160:161], s[36:37] op_sel_hi:[1,0]
	v_cvt_pk_bf16_f32 v4, v4, v5
	v_pk_mul_f32 v[12:13], v[156:157], s[36:37] op_sel_hi:[1,0]
	v_cvt_pk_bf16_f32 v5, v6, v7
	v_pk_mul_f32 v[14:15], v[154:155], s[36:37] op_sel_hi:[1,0]
	v_pk_mul_f32 v[16:17], v[138:139], s[36:37] op_sel_hi:[1,0]
	v_cvt_pk_bf16_f32 v6, v14, v15
	v_cvt_pk_bf16_f32 v7, v12, v13
	global_store_dwordx4 v[2:3], v[4:7], off
	v_pk_mul_f32 v[12:13], v[148:149], s[36:37] op_sel_hi:[1,0]
	v_pk_mul_f32 v[14:15], v[146:147], s[36:37] op_sel_hi:[1,0]
	v_pk_mul_f32 v[4:5], v[150:151], s[36:37] op_sel_hi:[1,0]
	v_pk_mul_f32 v[6:7], v[152:153], s[36:37] op_sel_hi:[1,0]
	v_cvt_pk_bf16_f32 v4, v4, v5
	s_nop 0
	v_cvt_pk_bf16_f32 v5, v6, v7
	v_cvt_pk_bf16_f32 v6, v14, v15
	v_cvt_pk_bf16_f32 v7, v12, v13
	global_store_dwordx4 v[2:3], v[4:7], off offset:256
	v_pk_mul_f32 v[14:15], v[140:141], s[36:37] op_sel_hi:[1,0]
	s_nop 0
	v_or_b32_e32 v4, 16, v8
	v_ashrrev_i32_e32 v5, 31, v4
	v_lshlrev_b64 v[4:5], 15, v[4:5]
	v_lshl_add_u64 v[4:5], s[12:13], 0, v[4:5]
	v_lshl_add_u64 v[12:13], v[4:5], 0, v[10:11]
	v_pk_mul_f32 v[4:5], v[142:143], s[36:37] op_sel_hi:[1,0]
	v_pk_mul_f32 v[6:7], v[144:145], s[36:37] op_sel_hi:[1,0]
	v_cvt_pk_bf16_f32 v4, v4, v5
	s_nop 0
	v_cvt_pk_bf16_f32 v5, v6, v7
	v_cvt_pk_bf16_f32 v6, v16, v17
	v_cvt_pk_bf16_f32 v7, v14, v15
	global_store_dwordx4 v[12:13], v[4:7], off
	v_pk_mul_f32 v[14:15], v[132:133], s[36:37] op_sel_hi:[1,0]
	v_pk_mul_f32 v[16:17], v[130:131], s[36:37] op_sel_hi:[1,0]
	v_pk_mul_f32 v[4:5], v[134:135], s[36:37] op_sel_hi:[1,0]
	v_pk_mul_f32 v[6:7], v[136:137], s[36:37] op_sel_hi:[1,0]
	v_cvt_pk_bf16_f32 v4, v4, v5
	s_nop 0
	v_cvt_pk_bf16_f32 v5, v6, v7
	v_cvt_pk_bf16_f32 v6, v16, v17
	v_cvt_pk_bf16_f32 v7, v14, v15
	global_store_dwordx4 v[12:13], v[4:7], off offset:256
	v_pk_mul_f32 v[14:15], v[120:121], s[36:37] op_sel_hi:[1,0]
	v_pk_mul_f32 v[16:17], v[118:119], s[36:37] op_sel_hi:[1,0]
	v_or_b32_e32 v4, 32, v8
	v_ashrrev_i32_e32 v5, 31, v4
	v_lshlrev_b64 v[4:5], 15, v[4:5]
	v_lshl_add_u64 v[4:5], s[12:13], 0, v[4:5]
	v_lshl_add_u64 v[12:13], v[4:5], 0, v[10:11]
	v_pk_mul_f32 v[4:5], v[126:127], s[36:37] op_sel_hi:[1,0]
	v_pk_mul_f32 v[6:7], v[128:129], s[36:37] op_sel_hi:[1,0]
	v_cvt_pk_bf16_f32 v4, v4, v5
	s_nop 0
	v_cvt_pk_bf16_f32 v5, v6, v7
	v_cvt_pk_bf16_f32 v6, v16, v17
	v_cvt_pk_bf16_f32 v7, v14, v15
	global_store_dwordx4 v[12:13], v[4:7], off
	v_pk_mul_f32 v[14:15], v[108:109], s[36:37] op_sel_hi:[1,0]
	v_pk_mul_f32 v[16:17], v[106:107], s[36:37] op_sel_hi:[1,0]
	v_pk_mul_f32 v[4:5], v[110:111], s[36:37] op_sel_hi:[1,0]
	v_pk_mul_f32 v[6:7], v[112:113], s[36:37] op_sel_hi:[1,0]
	v_cvt_pk_bf16_f32 v4, v4, v5
	s_nop 0
	v_cvt_pk_bf16_f32 v5, v6, v7
	v_cvt_pk_bf16_f32 v6, v16, v17
	v_cvt_pk_bf16_f32 v7, v14, v15
	global_store_dwordx4 v[12:13], v[4:7], off offset:256
	v_pk_mul_f32 v[12:13], v[82:83], s[36:37] op_sel_hi:[1,0]
	s_nop 0
	v_or_b32_e32 v4, 48, v8
	v_ashrrev_i32_e32 v5, 31, v4
	v_lshlrev_b64 v[4:5], 15, v[4:5]
	v_lshl_add_u64 v[4:5], s[12:13], 0, v[4:5]
	v_lshl_add_u64 v[8:9], v[4:5], 0, v[10:11]
	v_pk_mul_f32 v[6:7], v[92:93], s[36:37] op_sel_hi:[1,0]
	v_pk_mul_f32 v[4:5], v[90:91], s[36:37] op_sel_hi:[1,0]
	v_pk_mul_f32 v[10:11], v[84:85], s[36:37] op_sel_hi:[1,0]
	v_cvt_pk_bf16_f32 v4, v4, v5
	v_cvt_pk_bf16_f32 v5, v6, v7
	v_cvt_pk_bf16_f32 v6, v12, v13
	v_pk_mul_f32 v[12:13], v[74:75], s[36:37] op_sel_hi:[1,0]
	v_cvt_pk_bf16_f32 v7, v10, v11
	global_store_dwordx4 v[8:9], v[4:7], off
	v_pk_mul_f32 v[10:11], v[76:77], s[36:37] op_sel_hi:[1,0]
	s_nop 0
	v_pk_mul_f32 v[6:7], v[80:81], s[36:37] op_sel_hi:[1,0]
	v_pk_mul_f32 v[4:5], v[78:79], s[36:37] op_sel_hi:[1,0]
	s_nop 0
	v_cvt_pk_bf16_f32 v4, v4, v5
	v_cvt_pk_bf16_f32 v5, v6, v7
	v_cvt_pk_bf16_f32 v6, v12, v13
	v_cvt_pk_bf16_f32 v7, v10, v11
	global_store_dwordx4 v[8:9], v[4:7], off offset:256
	v_pk_mul_f32 v[10:11], v[116:117], s[36:37] op_sel_hi:[1,0]
	v_pk_mul_f32 v[12:13], v[114:115], s[36:37] op_sel_hi:[1,0]
	v_pk_mul_f32 v[6:7], v[124:125], s[36:37] op_sel_hi:[1,0]
	v_pk_mul_f32 v[4:5], v[122:123], s[36:37] op_sel_hi:[1,0]
	v_lshl_add_u64 v[8:9], v[2:3], 0, s[38:39]
	v_cvt_pk_bf16_f32 v4, v4, v5
	v_cvt_pk_bf16_f32 v5, v6, v7
	v_cvt_pk_bf16_f32 v6, v12, v13
	v_cvt_pk_bf16_f32 v7, v10, v11
	v_add_co_u32_e32 v10, vcc, s68, v2
	v_pk_mul_f32 v[12:13], v[98:99], s[36:37] op_sel_hi:[1,0]
	s_nop 0
	v_addc_co_u32_e32 v11, vcc, 0, v3, vcc
	global_store_dwordx4 v[10:11], v[4:7], off
	v_pk_mul_f32 v[10:11], v[100:101], s[36:37] op_sel_hi:[1,0]
	s_nop 0
	v_pk_mul_f32 v[6:7], v[104:105], s[36:37] op_sel_hi:[1,0]
	v_pk_mul_f32 v[4:5], v[102:103], s[36:37] op_sel_hi:[1,0]
	s_nop 0
	v_cvt_pk_bf16_f32 v4, v4, v5
	v_cvt_pk_bf16_f32 v5, v6, v7
	v_cvt_pk_bf16_f32 v6, v12, v13
	v_cvt_pk_bf16_f32 v7, v10, v11
	global_store_dwordx4 v[8:9], v[4:7], off offset:256
	v_pk_mul_f32 v[10:11], v[88:89], s[36:37] op_sel_hi:[1,0]
	v_pk_mul_f32 v[12:13], v[86:87], s[36:37] op_sel_hi:[1,0]
	v_pk_mul_f32 v[6:7], v[96:97], s[36:37] op_sel_hi:[1,0]
	v_pk_mul_f32 v[4:5], v[94:95], s[36:37] op_sel_hi:[1,0]
	v_lshl_add_u64 v[8:9], v[2:3], 0, s[40:41]
	v_cvt_pk_bf16_f32 v4, v4, v5
	v_cvt_pk_bf16_f32 v5, v6, v7
	v_cvt_pk_bf16_f32 v6, v12, v13
	v_cvt_pk_bf16_f32 v7, v10, v11
	v_add_co_u32_e32 v10, vcc, s69, v2
	v_pk_mul_f32 v[12:13], v[66:67], s[36:37] op_sel_hi:[1,0]
	s_nop 0
	v_addc_co_u32_e32 v11, vcc, 0, v3, vcc
	global_store_dwordx4 v[10:11], v[4:7], off
	v_pk_mul_f32 v[10:11], v[68:69], s[36:37] op_sel_hi:[1,0]
	s_nop 0
	v_pk_mul_f32 v[6:7], v[72:73], s[36:37] op_sel_hi:[1,0]
	v_pk_mul_f32 v[4:5], v[70:71], s[36:37] op_sel_hi:[1,0]
	s_nop 0
	v_cvt_pk_bf16_f32 v4, v4, v5
	v_cvt_pk_bf16_f32 v5, v6, v7
	v_cvt_pk_bf16_f32 v6, v12, v13
	v_cvt_pk_bf16_f32 v7, v10, v11
	global_store_dwordx4 v[8:9], v[4:7], off offset:256
	v_pk_mul_f32 v[10:11], v[60:61], s[36:37] op_sel_hi:[1,0]
	v_pk_mul_f32 v[12:13], v[58:59], s[36:37] op_sel_hi:[1,0]
	v_pk_mul_f32 v[6:7], v[64:65], s[36:37] op_sel_hi:[1,0]
	v_pk_mul_f32 v[4:5], v[62:63], s[36:37] op_sel_hi:[1,0]
	v_lshl_add_u64 v[8:9], v[2:3], 0, s[42:43]
	v_cvt_pk_bf16_f32 v4, v4, v5
	v_cvt_pk_bf16_f32 v5, v6, v7
	v_cvt_pk_bf16_f32 v6, v12, v13
	v_cvt_pk_bf16_f32 v7, v10, v11
	v_add_co_u32_e32 v10, vcc, s70, v2
	v_pk_mul_f32 v[12:13], v[50:51], s[36:37] op_sel_hi:[1,0]
	s_nop 0
	v_addc_co_u32_e32 v11, vcc, 0, v3, vcc
	global_store_dwordx4 v[10:11], v[4:7], off
	v_pk_mul_f32 v[10:11], v[52:53], s[36:37] op_sel_hi:[1,0]
	s_nop 0
	v_pk_mul_f32 v[4:5], v[54:55], s[36:37] op_sel_hi:[1,0]
	v_pk_mul_f32 v[6:7], v[56:57], s[36:37] op_sel_hi:[1,0]
	v_cvt_pk_bf16_f32 v4, v4, v5
	s_nop 0
	v_cvt_pk_bf16_f32 v5, v6, v7
	v_cvt_pk_bf16_f32 v6, v12, v13
	v_cvt_pk_bf16_f32 v7, v10, v11
	global_store_dwordx4 v[8:9], v[4:7], off offset:256
	v_lshl_add_u64 v[8:9], v[2:3], 0, s[44:45]
	v_add_co_u32_e32 v2, vcc, s71, v2
	v_pk_mul_f32 v[4:5], v[46:47], s[36:37] op_sel_hi:[1,0]
	v_pk_mul_f32 v[6:7], v[48:49], s[36:37] op_sel_hi:[1,0]
	v_cvt_pk_bf16_f32 v4, v4, v5
	v_addc_co_u32_e32 v3, vcc, 0, v3, vcc
	v_cvt_pk_bf16_f32 v5, v6, v7
	v_pk_mul_f32 v[10:11], v[44:45], s[36:37] op_sel_hi:[1,0]
	v_pk_mul_f32 v[12:13], v[42:43], s[36:37] op_sel_hi:[1,0]
	s_andn2_b64 vcc, exec, s[4:5]
	v_cvt_pk_bf16_f32 v6, v12, v13
	v_cvt_pk_bf16_f32 v7, v10, v11
	global_store_dwordx4 v[2:3], v[4:7], off
	v_pk_mul_f32 v[2:3], v[38:39], s[36:37] op_sel_hi:[1,0]
	s_mov_b64 s[4:5], -1
	v_pk_mul_f32 v[4:5], v[40:41], s[36:37] op_sel_hi:[1,0]
	v_pk_mul_f32 v[6:7], v[36:37], s[36:37] op_sel_hi:[1,0]
	v_pk_mul_f32 v[10:11], v[34:35], s[36:37] op_sel_hi:[1,0]
	v_cvt_pk_bf16_f32 v2, v2, v3
	v_cvt_pk_bf16_f32 v3, v4, v5
	s_nop 0
	v_cvt_pk_bf16_f32 v4, v10, v11
	v_cvt_pk_bf16_f32 v5, v6, v7
	global_store_dwordx4 v[8:9], v[2:5], off offset:256
	s_cbranch_vccnz .LBB0_278
	s_andn2_b64 vcc, exec, s[6:7]
	s_cbranch_vccnz .LBB0_277
	s_branch .LBB0_277
.LBB0_288:
	s_waitcnt vmcnt(0)
	v_readlane_b32 s80, v255, 5
	s_cmp_lg_u64 s[16:17], 0
	s_cbranch_scc0 .Lmy_na_1
	s_barrier

.LBB0_309:
	v_lshl_add_u32 v142, s50, 8, v1
	v_lshl_or_b32 v144, s72, 8, v254
	v_ashrrev_i32_e32 v143, 31, v142
	v_ashrrev_i32_e32 v145, 31, v144
	v_lshlrev_b64 v[146:147], 13, v[142:143]
	v_lshl_add_u64 v[146:147], s[12:13], 0, v[146:147]
	v_lshlrev_b64 v[144:145], 1, v[144:145]
	v_lshl_add_u64 v[146:147], v[146:147], 0, v[144:145]
	v_cvt_pk_bf16_f32 v122, v122, v123
	v_cvt_pk_bf16_f32 v123, v124, v125
	v_cvt_pk_bf16_f32 v124, v114, v115
	v_cvt_pk_bf16_f32 v125, v116, v117
	global_store_dwordx4 v[146:147], v[122:125], off
	v_cvt_pk_bf16_f32 v114, v126, v127
	v_cvt_pk_bf16_f32 v115, v128, v129
	v_cvt_pk_bf16_f32 v116, v118, v119
	v_cvt_pk_bf16_f32 v117, v120, v121
	global_store_dwordx4 v[146:147], v[114:117], off offset:256
	v_cvt_pk_bf16_f32 v106, v106, v107
	v_cvt_pk_bf16_f32 v107, v108, v109
	v_cvt_pk_bf16_f32 v108, v98, v99
	v_cvt_pk_bf16_f32 v109, v100, v101
	s_nop 1
	v_or_b32_e32 v114, 16, v142
	v_ashrrev_i32_e32 v115, 31, v114
	v_lshlrev_b64 v[114:115], 13, v[114:115]
	v_lshl_add_u64 v[114:115], s[12:13], 0, v[114:115]
	v_lshl_add_u64 v[114:115], v[114:115], 0, v[144:145]
	global_store_dwordx4 v[114:115], v[106:109], off
	v_cvt_pk_bf16_f32 v98, v110, v111
	v_cvt_pk_bf16_f32 v99, v112, v113
	v_cvt_pk_bf16_f32 v100, v102, v103
	v_cvt_pk_bf16_f32 v101, v104, v105
	global_store_dwordx4 v[114:115], v[98:101], off offset:256
	v_cvt_pk_bf16_f32 v90, v90, v91
	v_cvt_pk_bf16_f32 v91, v92, v93
	v_cvt_pk_bf16_f32 v92, v82, v83
	v_cvt_pk_bf16_f32 v93, v84, v85
	s_nop 1
	v_or_b32_e32 v98, 32, v142
	v_ashrrev_i32_e32 v99, 31, v98
	v_lshlrev_b64 v[98:99], 13, v[98:99]
	v_lshl_add_u64 v[98:99], s[12:13], 0, v[98:99]
	v_lshl_add_u64 v[98:99], v[98:99], 0, v[144:145]
	global_store_dwordx4 v[98:99], v[90:93], off
	v_cvt_pk_bf16_f32 v82, v94, v95
	v_cvt_pk_bf16_f32 v83, v96, v97
	v_cvt_pk_bf16_f32 v84, v86, v87
	v_cvt_pk_bf16_f32 v85, v88, v89
	global_store_dwordx4 v[98:99], v[82:85], off offset:256
	v_cvt_pk_bf16_f32 v58, v58, v59
	v_cvt_pk_bf16_f32 v59, v60, v61
	v_cvt_pk_bf16_f32 v60, v50, v51
	v_cvt_pk_bf16_f32 v61, v52, v53
	s_nop 1
	v_or_b32_e32 v82, 48, v142
	v_ashrrev_i32_e32 v83, 31, v82
	v_lshlrev_b64 v[82:83], 13, v[82:83]
	v_lshl_add_u64 v[82:83], s[12:13], 0, v[82:83]
	v_lshl_add_u64 v[82:83], v[82:83], 0, v[144:145]
	global_store_dwordx4 v[82:83], v[58:61], off
	v_cvt_pk_bf16_f32 v50, v62, v63
	v_cvt_pk_bf16_f32 v51, v64, v65
	v_cvt_pk_bf16_f32 v52, v54, v55
	v_cvt_pk_bf16_f32 v53, v56, v57
	v_add_co_u32_e32 v56, vcc, s68, v146
	global_store_dwordx4 v[82:83], v[50:53], off offset:256
	v_lshl_add_u64 v[54:55], v[146:147], 0, s[8:9]
	v_addc_co_u32_e32 v57, vcc, 0, v147, vcc
	v_cvt_pk_bf16_f32 v50, v78, v79
	v_cvt_pk_bf16_f32 v51, v80, v81
	v_cvt_pk_bf16_f32 v52, v70, v71
	v_cvt_pk_bf16_f32 v53, v72, v73
	global_store_dwordx4 v[56:57], v[50:53], off
	s_nop 1
	v_cvt_pk_bf16_f32 v50, v74, v75
	v_cvt_pk_bf16_f32 v51, v76, v77
	v_cvt_pk_bf16_f32 v52, v66, v67
	v_cvt_pk_bf16_f32 v53, v68, v69
	global_store_dwordx4 v[54:55], v[50:53], off offset:256
	v_cvt_pk_bf16_f32 v46, v46, v47
	v_cvt_pk_bf16_f32 v47, v48, v49
	v_cvt_pk_bf16_f32 v48, v38, v39
	v_add_co_u32_e32 v38, vcc, s69, v146
	s_nop 0
	v_lshl_add_u64 v[50:51], v[146:147], 0, s[36:37]
	v_addc_co_u32_e32 v39, vcc, 0, v147, vcc
	v_cvt_pk_bf16_f32 v49, v40, v41
	global_store_dwordx4 v[38:39], v[46:49], off
	v_cvt_pk_bf16_f32 v38, v42, v43
	v_cvt_pk_bf16_f32 v39, v44, v45
	v_cvt_pk_bf16_f32 v40, v34, v35
	v_cvt_pk_bf16_f32 v41, v36, v37
	global_store_dwordx4 v[50:51], v[38:41], off offset:256
	v_cvt_pk_bf16_f32 v30, v30, v31
	v_cvt_pk_bf16_f32 v31, v32, v33
	v_cvt_pk_bf16_f32 v32, v22, v23
	v_add_co_u32_e32 v22, vcc, s70, v146
	v_lshl_add_u64 v[34:35], v[146:147], 0, s[38:39]
	s_nop 0
	v_addc_co_u32_e32 v23, vcc, 0, v147, vcc
	v_cvt_pk_bf16_f32 v33, v24, v25
	global_store_dwordx4 v[22:23], v[30:33], off
	v_cvt_pk_bf16_f32 v22, v26, v27
	v_cvt_pk_bf16_f32 v23, v28, v29
	v_cvt_pk_bf16_f32 v24, v18, v19
	v_cvt_pk_bf16_f32 v25, v20, v21
	global_store_dwordx4 v[34:35], v[22:25], off offset:256
	v_cvt_pk_bf16_f32 v14, v14, v15
	v_cvt_pk_bf16_f32 v15, v16, v17
	v_cvt_pk_bf16_f32 v16, v6, v7
	v_add_co_u32_e32 v6, vcc, s71, v146
	v_lshl_add_u64 v[18:19], v[146:147], 0, s[40:41]
	s_nop 0
	v_addc_co_u32_e32 v7, vcc, 0, v147, vcc
	s_andn2_b64 vcc, exec, s[4:5]
	s_mov_b64 s[4:5], -1
	v_cvt_pk_bf16_f32 v17, v8, v9
	global_store_dwordx4 v[6:7], v[14:17], off
	v_cvt_pk_bf16_f32 v6, v10, v11
	v_cvt_pk_bf16_f32 v7, v12, v13
	v_cvt_pk_bf16_f32 v8, v2, v3
	v_cvt_pk_bf16_f32 v9, v4, v5
	global_store_dwordx4 v[18:19], v[6:9], off offset:256
	s_cbranch_vccnz .LBB0_298
	s_andn2_b64 vcc, exec, s[10:11]
	s_cbranch_vccnz .LBB0_297
	s_branch .LBB0_297

.LBB0_750:
	v_lshl_add_u32 v142, s50, 8, v1
	v_lshl_or_b32 v144, s74, 8, v254
	v_ashrrev_i32_e32 v143, 31, v142
	v_ashrrev_i32_e32 v145, 31, v144
	v_lshlrev_b64 v[146:147], 13, v[142:143]
	v_lshl_add_u64 v[146:147], s[6:7], 0, v[146:147]
	v_lshlrev_b64 v[144:145], 1, v[144:145]
	v_lshl_add_u64 v[146:147], v[146:147], 0, v[144:145]
	v_cvt_pk_bf16_f32 v122, v122, v123
	v_cvt_pk_bf16_f32 v123, v124, v125
	v_cvt_pk_bf16_f32 v124, v114, v115
	v_cvt_pk_bf16_f32 v125, v116, v117
	global_store_dwordx4 v[146:147], v[122:125], off
	v_cvt_pk_bf16_f32 v114, v126, v127
	v_cvt_pk_bf16_f32 v115, v128, v129
	v_cvt_pk_bf16_f32 v116, v118, v119
	v_cvt_pk_bf16_f32 v117, v120, v121
	global_store_dwordx4 v[146:147], v[114:117], off offset:256
	v_cvt_pk_bf16_f32 v106, v106, v107
	v_cvt_pk_bf16_f32 v107, v108, v109
	v_cvt_pk_bf16_f32 v108, v98, v99
	v_cvt_pk_bf16_f32 v109, v100, v101
	s_nop 1
	v_or_b32_e32 v114, 16, v142
	v_ashrrev_i32_e32 v115, 31, v114
	v_lshlrev_b64 v[114:115], 13, v[114:115]
	v_lshl_add_u64 v[114:115], s[6:7], 0, v[114:115]
	v_lshl_add_u64 v[114:115], v[114:115], 0, v[144:145]
	global_store_dwordx4 v[114:115], v[106:109], off
	v_cvt_pk_bf16_f32 v98, v110, v111
	v_cvt_pk_bf16_f32 v99, v112, v113
	v_cvt_pk_bf16_f32 v100, v102, v103
	v_cvt_pk_bf16_f32 v101, v104, v105
	global_store_dwordx4 v[114:115], v[98:101], off offset:256
	v_cvt_pk_bf16_f32 v90, v90, v91
	v_cvt_pk_bf16_f32 v91, v92, v93
	v_cvt_pk_bf16_f32 v92, v82, v83
	v_cvt_pk_bf16_f32 v93, v84, v85
	s_nop 1
	v_or_b32_e32 v98, 32, v142
	v_ashrrev_i32_e32 v99, 31, v98
	v_lshlrev_b64 v[98:99], 13, v[98:99]
	v_lshl_add_u64 v[98:99], s[6:7], 0, v[98:99]
	v_lshl_add_u64 v[98:99], v[98:99], 0, v[144:145]
	global_store_dwordx4 v[98:99], v[90:93], off
	v_cvt_pk_bf16_f32 v82, v94, v95
	v_cvt_pk_bf16_f32 v83, v96, v97
	v_cvt_pk_bf16_f32 v84, v86, v87
	v_cvt_pk_bf16_f32 v85, v88, v89
	global_store_dwordx4 v[98:99], v[82:85], off offset:256
	v_cvt_pk_bf16_f32 v58, v58, v59
	v_cvt_pk_bf16_f32 v59, v60, v61
	v_cvt_pk_bf16_f32 v60, v50, v51
	v_cvt_pk_bf16_f32 v61, v52, v53
	s_nop 1
	v_or_b32_e32 v82, 48, v142
	v_ashrrev_i32_e32 v83, 31, v82
	v_lshlrev_b64 v[82:83], 13, v[82:83]
	v_lshl_add_u64 v[82:83], s[6:7], 0, v[82:83]
	v_lshl_add_u64 v[82:83], v[82:83], 0, v[144:145]
	global_store_dwordx4 v[82:83], v[58:61], off
	v_cvt_pk_bf16_f32 v50, v62, v63
	v_cvt_pk_bf16_f32 v51, v64, v65
	v_cvt_pk_bf16_f32 v52, v54, v55
	v_cvt_pk_bf16_f32 v53, v56, v57
	v_add_co_u32_e32 v56, vcc, s70, v146
	global_store_dwordx4 v[82:83], v[50:53], off offset:256
	v_lshl_add_u64 v[54:55], v[146:147], 0, s[34:35]
	v_addc_co_u32_e32 v57, vcc, 0, v147, vcc
	v_cvt_pk_bf16_f32 v50, v78, v79
	v_cvt_pk_bf16_f32 v51, v80, v81
	v_cvt_pk_bf16_f32 v52, v70, v71
	v_cvt_pk_bf16_f32 v53, v72, v73
	global_store_dwordx4 v[56:57], v[50:53], off
	s_nop 1
	v_cvt_pk_bf16_f32 v50, v74, v75
	v_cvt_pk_bf16_f32 v51, v76, v77
	v_cvt_pk_bf16_f32 v52, v66, v67
	v_cvt_pk_bf16_f32 v53, v68, v69
	global_store_dwordx4 v[54:55], v[50:53], off offset:256
	v_cvt_pk_bf16_f32 v46, v46, v47
	v_cvt_pk_bf16_f32 v47, v48, v49
	v_cvt_pk_bf16_f32 v48, v38, v39
	v_add_co_u32_e32 v38, vcc, s71, v146
	s_nop 0
	v_lshl_add_u64 v[50:51], v[146:147], 0, s[36:37]
	v_addc_co_u32_e32 v39, vcc, 0, v147, vcc
	v_cvt_pk_bf16_f32 v49, v40, v41
	global_store_dwordx4 v[38:39], v[46:49], off
	v_cvt_pk_bf16_f32 v38, v42, v43
	v_cvt_pk_bf16_f32 v39, v44, v45
	v_cvt_pk_bf16_f32 v40, v34, v35
	v_cvt_pk_bf16_f32 v41, v36, v37
	global_store_dwordx4 v[50:51], v[38:41], off offset:256
	v_cvt_pk_bf16_f32 v30, v30, v31
	v_cvt_pk_bf16_f32 v31, v32, v33
	v_cvt_pk_bf16_f32 v32, v22, v23
	v_add_co_u32_e32 v22, vcc, s72, v146
	v_lshl_add_u64 v[34:35], v[146:147], 0, s[38:39]
	s_nop 0
	v_addc_co_u32_e32 v23, vcc, 0, v147, vcc
	v_cvt_pk_bf16_f32 v33, v24, v25
	global_store_dwordx4 v[22:23], v[30:33], off
	v_cvt_pk_bf16_f32 v22, v26, v27
	v_cvt_pk_bf16_f32 v23, v28, v29
	v_cvt_pk_bf16_f32 v24, v18, v19
	v_cvt_pk_bf16_f32 v25, v20, v21
	global_store_dwordx4 v[34:35], v[22:25], off offset:256
	v_cvt_pk_bf16_f32 v14, v14, v15
	v_cvt_pk_bf16_f32 v15, v16, v17
	v_cvt_pk_bf16_f32 v16, v6, v7
	v_add_co_u32_e32 v6, vcc, s73, v146
	v_lshl_add_u64 v[18:19], v[146:147], 0, s[40:41]
	s_nop 0
	v_addc_co_u32_e32 v7, vcc, 0, v147, vcc
	s_andn2_b64 vcc, exec, s[4:5]
	s_mov_b64 s[4:5], -1
	v_cvt_pk_bf16_f32 v17, v8, v9
	global_store_dwordx4 v[6:7], v[14:17], off
	v_cvt_pk_bf16_f32 v6, v10, v11
	v_cvt_pk_bf16_f32 v7, v12, v13
	v_cvt_pk_bf16_f32 v8, v2, v3
	v_cvt_pk_bf16_f32 v9, v4, v5
	global_store_dwordx4 v[18:19], v[6:9], off offset:256
	s_cbranch_vccnz .LBB0_739
	s_andn2_b64 vcc, exec, s[10:11]
	s_cbranch_vccnz .LBB0_738
	s_branch .LBB0_738

.LBB0_774:
	v_lshl_add_u32 v4, s54, 8, v1
	v_lshl_or_b32 v2, s73, 8, v187
	v_ashrrev_i32_e32 v5, 31, v4
	v_ashrrev_i32_e32 v3, 31, v2
	v_lshlrev_b64 v[6:7], 13, v[4:5]
	v_lshl_add_u64 v[8:9], s[6:7], 0, v[6:7]
	v_lshlrev_b64 v[6:7], 1, v[2:3]
	v_lshl_add_u64 v[2:3], v[8:9], 0, v[6:7]
	global_load_dwordx4 v[8:11], v[2:3], off
	v_pk_mul_f32 v[12:13], v[156:157], s[36:37] op_sel_hi:[1,0]
	v_pk_mul_f32 v[14:15], v[154:155], s[36:37] op_sel_hi:[1,0]
	v_pk_mul_f32 v[16:17], v[160:161], s[36:37] op_sel_hi:[1,0]
	v_pk_mul_f32 v[18:19], v[158:159], s[36:37] op_sel_hi:[1,0]
	v_or_b32_e32 v24, 16, v4
	v_ashrrev_i32_e32 v25, 31, v24
	v_lshlrev_b64 v[24:25], 13, v[24:25]
	v_lshl_add_u64 v[24:25], s[6:7], 0, v[24:25]
	v_lshl_add_u64 v[24:25], v[24:25], 0, v[6:7]
	v_or_b32_e32 v26, 32, v4
	v_ashrrev_i32_e32 v27, 31, v26
	v_lshlrev_b64 v[26:27], 13, v[26:27]
	v_lshl_add_u64 v[26:27], s[6:7], 0, v[26:27]
	v_lshl_add_u64 v[26:27], v[26:27], 0, v[6:7]
	v_or_b32_e32 v4, 48, v4
	s_waitcnt vmcnt(0)
	v_lshlrev_b32_e32 v5, 16, v8
	v_and_b32_e32 v8, 0xffff0000, v8
	v_lshlrev_b32_e32 v20, 16, v9
	v_and_b32_e32 v9, 0xffff0000, v9
	v_lshlrev_b32_e32 v21, 16, v10
	v_and_b32_e32 v10, 0xffff0000, v10
	v_lshlrev_b32_e32 v22, 16, v11
	v_and_b32_e32 v11, 0xffff0000, v11
	v_add_f32_e32 v5, v14, v5
	v_add_f32_e32 v8, v15, v8
	v_add_f32_e32 v12, v12, v20
	v_add_f32_e32 v9, v13, v9
	v_add_f32_e32 v13, v18, v21
	v_add_f32_e32 v10, v19, v10
	v_add_f32_e32 v14, v16, v22
	v_add_f32_e32 v11, v17, v11
	v_cvt_pk_bf16_f32 v8, v5, v8
	v_cvt_pk_bf16_f32 v9, v12, v9
	v_cvt_pk_bf16_f32 v10, v13, v10
	v_cvt_pk_bf16_f32 v11, v14, v11
	global_load_dwordx4 v[12:15], v[2:3], off offset:256
	v_pk_mul_f32 v[16:17], v[148:149], s[36:37] op_sel_hi:[1,0]
	v_pk_mul_f32 v[18:19], v[146:147], s[36:37] op_sel_hi:[1,0]
	v_pk_mul_f32 v[20:21], v[152:153], s[36:37] op_sel_hi:[1,0]
	v_pk_mul_f32 v[22:23], v[150:151], s[36:37] op_sel_hi:[1,0]
	global_store_dwordx4 v[2:3], v[8:11], off
	s_waitcnt vmcnt(1)
	v_lshlrev_b32_e32 v5, 16, v12
	v_and_b32_e32 v8, 0xffff0000, v12
	v_lshlrev_b32_e32 v9, 16, v13
	v_and_b32_e32 v10, 0xffff0000, v13
	v_lshlrev_b32_e32 v11, 16, v14
	v_and_b32_e32 v12, 0xffff0000, v14
	v_lshlrev_b32_e32 v13, 16, v15
	v_and_b32_e32 v14, 0xffff0000, v15
	v_add_f32_e32 v8, v19, v8
	v_add_f32_e32 v9, v16, v9
	v_add_f32_e32 v10, v17, v10
	v_add_f32_e32 v11, v22, v11
	v_add_f32_e32 v12, v23, v12
	v_add_f32_e32 v13, v20, v13
	v_add_f32_e32 v14, v21, v14
	v_add_f32_e32 v5, v18, v5
	v_cvt_pk_bf16_f32 v8, v5, v8
	v_cvt_pk_bf16_f32 v9, v9, v10
	v_cvt_pk_bf16_f32 v10, v11, v12
	v_cvt_pk_bf16_f32 v11, v13, v14
	global_load_dwordx4 v[12:15], v[24:25], off
	v_pk_mul_f32 v[16:17], v[144:145], s[36:37] op_sel_hi:[1,0]
	v_pk_mul_f32 v[18:19], v[142:143], s[36:37] op_sel_hi:[1,0]
	v_pk_mul_f32 v[20:21], v[140:141], s[36:37] op_sel_hi:[1,0]
	v_pk_mul_f32 v[22:23], v[138:139], s[36:37] op_sel_hi:[1,0]
	global_store_dwordx4 v[2:3], v[8:11], off offset:256
	s_waitcnt vmcnt(1)
	v_lshlrev_b32_e32 v5, 16, v12
	v_and_b32_e32 v8, 0xffff0000, v12
	v_lshlrev_b32_e32 v9, 16, v13
	v_and_b32_e32 v10, 0xffff0000, v13
	v_lshlrev_b32_e32 v11, 16, v14
	v_and_b32_e32 v12, 0xffff0000, v14
	v_lshlrev_b32_e32 v13, 16, v15
	v_and_b32_e32 v14, 0xffff0000, v15
	v_add_f32_e32 v8, v19, v8
	v_add_f32_e32 v9, v16, v9
	v_add_f32_e32 v10, v17, v10
	v_add_f32_e32 v11, v22, v11
	v_add_f32_e32 v12, v23, v12
	v_add_f32_e32 v13, v20, v13
	v_add_f32_e32 v14, v21, v14
	v_add_f32_e32 v5, v18, v5
	v_cvt_pk_bf16_f32 v8, v5, v8
	v_cvt_pk_bf16_f32 v9, v9, v10
	v_cvt_pk_bf16_f32 v10, v11, v12
	v_cvt_pk_bf16_f32 v11, v13, v14
	global_load_dwordx4 v[12:15], v[24:25], off offset:256
	v_pk_mul_f32 v[16:17], v[136:137], s[36:37] op_sel_hi:[1,0]
	v_pk_mul_f32 v[18:19], v[134:135], s[36:37] op_sel_hi:[1,0]
	v_pk_mul_f32 v[20:21], v[132:133], s[36:37] op_sel_hi:[1,0]
	v_pk_mul_f32 v[22:23], v[130:131], s[36:37] op_sel_hi:[1,0]
	global_store_dwordx4 v[24:25], v[8:11], off
	s_waitcnt vmcnt(1)
	v_lshlrev_b32_e32 v5, 16, v12
	v_and_b32_e32 v8, 0xffff0000, v12
	v_lshlrev_b32_e32 v9, 16, v13
	v_and_b32_e32 v10, 0xffff0000, v13
	v_lshlrev_b32_e32 v11, 16, v14
	v_and_b32_e32 v12, 0xffff0000, v14
	v_lshlrev_b32_e32 v13, 16, v15
	v_and_b32_e32 v14, 0xffff0000, v15
	v_add_f32_e32 v8, v19, v8
	v_add_f32_e32 v9, v16, v9
	v_add_f32_e32 v10, v17, v10
	v_add_f32_e32 v11, v22, v11
	v_add_f32_e32 v12, v23, v12
	v_add_f32_e32 v13, v20, v13
	v_add_f32_e32 v14, v21, v14
	v_add_f32_e32 v5, v18, v5
	v_cvt_pk_bf16_f32 v8, v5, v8
	v_cvt_pk_bf16_f32 v9, v9, v10
	v_cvt_pk_bf16_f32 v10, v11, v12
	v_cvt_pk_bf16_f32 v11, v13, v14
	global_load_dwordx4 v[12:15], v[26:27], off
	v_pk_mul_f32 v[16:17], v[128:129], s[36:37] op_sel_hi:[1,0]
	v_pk_mul_f32 v[18:19], v[126:127], s[36:37] op_sel_hi:[1,0]
	v_pk_mul_f32 v[20:21], v[124:125], s[36:37] op_sel_hi:[1,0]
	v_pk_mul_f32 v[22:23], v[122:123], s[36:37] op_sel_hi:[1,0]
	global_store_dwordx4 v[24:25], v[8:11], off offset:256
	s_waitcnt vmcnt(1)
	v_lshlrev_b32_e32 v5, 16, v12
	v_and_b32_e32 v8, 0xffff0000, v12
	v_lshlrev_b32_e32 v9, 16, v13
	v_and_b32_e32 v10, 0xffff0000, v13
	v_lshlrev_b32_e32 v11, 16, v14
	v_and_b32_e32 v12, 0xffff0000, v14
	v_lshlrev_b32_e32 v13, 16, v15
	v_and_b32_e32 v14, 0xffff0000, v15
	v_add_f32_e32 v8, v19, v8
	v_add_f32_e32 v9, v16, v9
	v_add_f32_e32 v10, v17, v10
	v_add_f32_e32 v11, v22, v11
	v_add_f32_e32 v12, v23, v12
	v_add_f32_e32 v13, v20, v13
	v_add_f32_e32 v14, v21, v14
	v_add_f32_e32 v5, v18, v5
	v_cvt_pk_bf16_f32 v8, v5, v8
	v_cvt_pk_bf16_f32 v9, v9, v10
	v_cvt_pk_bf16_f32 v10, v11, v12
	v_cvt_pk_bf16_f32 v11, v13, v14
	global_load_dwordx4 v[12:15], v[26:27], off offset:256
	v_ashrrev_i32_e32 v5, 31, v4
	v_lshlrev_b64 v[4:5], 13, v[4:5]
	v_lshl_add_u64 v[4:5], s[6:7], 0, v[4:5]
	v_pk_mul_f32 v[16:17], v[120:121], s[36:37] op_sel_hi:[1,0]
	v_pk_mul_f32 v[18:19], v[118:119], s[36:37] op_sel_hi:[1,0]
	v_pk_mul_f32 v[20:21], v[116:117], s[36:37] op_sel_hi:[1,0]
	v_pk_mul_f32 v[22:23], v[114:115], s[36:37] op_sel_hi:[1,0]
	v_lshl_add_u64 v[24:25], v[4:5], 0, v[6:7]
	global_store_dwordx4 v[26:27], v[8:11], off
	s_waitcnt vmcnt(1)
	v_lshlrev_b32_e32 v4, 16, v12
	v_and_b32_e32 v5, 0xffff0000, v12
	v_lshlrev_b32_e32 v6, 16, v13
	v_and_b32_e32 v7, 0xffff0000, v13
	v_lshlrev_b32_e32 v8, 16, v14
	v_and_b32_e32 v9, 0xffff0000, v14
	v_lshlrev_b32_e32 v10, 16, v15
	v_and_b32_e32 v11, 0xffff0000, v15
	v_add_f32_e32 v4, v18, v4
	v_add_f32_e32 v5, v19, v5
	v_add_f32_e32 v6, v16, v6
	v_add_f32_e32 v7, v17, v7
	v_add_f32_e32 v8, v22, v8
	v_add_f32_e32 v9, v23, v9
	v_add_f32_e32 v10, v20, v10
	v_add_f32_e32 v11, v21, v11
	v_cvt_pk_bf16_f32 v4, v4, v5
	v_cvt_pk_bf16_f32 v5, v6, v7
	v_cvt_pk_bf16_f32 v6, v8, v9
	v_cvt_pk_bf16_f32 v7, v10, v11
	global_load_dwordx4 v[8:11], v[24:25], off
	v_pk_mul_f32 v[12:13], v[112:113], s[36:37] op_sel_hi:[1,0]
	v_pk_mul_f32 v[14:15], v[110:111], s[36:37] op_sel_hi:[1,0]
	v_pk_mul_f32 v[16:17], v[108:109], s[36:37] op_sel_hi:[1,0]
	v_pk_mul_f32 v[18:19], v[106:107], s[36:37] op_sel_hi:[1,0]
	global_store_dwordx4 v[26:27], v[4:7], off offset:256
	v_add_co_u32_e32 v20, vcc, s69, v2
	v_lshl_add_u64 v[22:23], v[2:3], 0, s[38:39]
	s_nop 0
	v_addc_co_u32_e32 v21, vcc, 0, v3, vcc
	s_waitcnt vmcnt(1)
	v_lshlrev_b32_e32 v4, 16, v8
	v_and_b32_e32 v5, 0xffff0000, v8
	v_lshlrev_b32_e32 v6, 16, v9
	v_and_b32_e32 v7, 0xffff0000, v9
	v_lshlrev_b32_e32 v8, 16, v10
	v_and_b32_e32 v9, 0xffff0000, v10
	v_lshlrev_b32_e32 v10, 16, v11
	v_and_b32_e32 v11, 0xffff0000, v11
	v_add_f32_e32 v4, v14, v4
	v_add_f32_e32 v5, v15, v5
	v_add_f32_e32 v6, v12, v6
	v_add_f32_e32 v7, v13, v7
	v_add_f32_e32 v8, v18, v8
	v_add_f32_e32 v9, v19, v9
	v_add_f32_e32 v10, v16, v10
	v_add_f32_e32 v11, v17, v11
	v_cvt_pk_bf16_f32 v4, v4, v5
	v_cvt_pk_bf16_f32 v5, v6, v7
	v_cvt_pk_bf16_f32 v6, v8, v9
	v_cvt_pk_bf16_f32 v7, v10, v11
	global_load_dwordx4 v[8:11], v[24:25], off offset:256
	v_pk_mul_f32 v[12:13], v[96:97], s[36:37] op_sel_hi:[1,0]
	v_pk_mul_f32 v[14:15], v[94:95], s[36:37] op_sel_hi:[1,0]
	v_pk_mul_f32 v[16:17], v[92:93], s[36:37] op_sel_hi:[1,0]
	v_pk_mul_f32 v[18:19], v[90:91], s[36:37] op_sel_hi:[1,0]
	global_store_dwordx4 v[24:25], v[4:7], off
	s_waitcnt vmcnt(1)
	s_nop 0
	v_lshlrev_b32_e32 v4, 16, v8
	v_and_b32_e32 v5, 0xffff0000, v8
	v_lshlrev_b32_e32 v6, 16, v9
	v_and_b32_e32 v7, 0xffff0000, v9
	v_lshlrev_b32_e32 v8, 16, v10
	v_and_b32_e32 v9, 0xffff0000, v10
	v_lshlrev_b32_e32 v10, 16, v11
	v_and_b32_e32 v11, 0xffff0000, v11
	v_add_f32_e32 v4, v14, v4
	v_add_f32_e32 v5, v15, v5
	v_add_f32_e32 v6, v12, v6
	v_add_f32_e32 v7, v13, v7
	v_add_f32_e32 v8, v18, v8
	v_add_f32_e32 v9, v19, v9
	v_add_f32_e32 v10, v16, v10
	v_add_f32_e32 v11, v17, v11
	v_cvt_pk_bf16_f32 v4, v4, v5
	v_cvt_pk_bf16_f32 v5, v6, v7
	v_cvt_pk_bf16_f32 v6, v8, v9
	v_cvt_pk_bf16_f32 v7, v10, v11
	global_load_dwordx4 v[8:11], v[20:21], off
	v_pk_mul_f32 v[12:13], v[104:105], s[36:37] op_sel_hi:[1,0]
	v_pk_mul_f32 v[14:15], v[102:103], s[36:37] op_sel_hi:[1,0]
	v_pk_mul_f32 v[16:17], v[100:101], s[36:37] op_sel_hi:[1,0]
	v_pk_mul_f32 v[18:19], v[98:99], s[36:37] op_sel_hi:[1,0]
	global_store_dwordx4 v[24:25], v[4:7], off offset:256
	v_add_co_u32_e32 v24, vcc, s70, v2
	s_waitcnt vmcnt(1)
	v_lshlrev_b32_e32 v4, 16, v8
	v_and_b32_e32 v5, 0xffff0000, v8
	v_lshlrev_b32_e32 v6, 16, v9
	v_and_b32_e32 v7, 0xffff0000, v9
	v_lshlrev_b32_e32 v8, 16, v10
	v_and_b32_e32 v9, 0xffff0000, v10
	v_lshlrev_b32_e32 v10, 16, v11
	v_and_b32_e32 v11, 0xffff0000, v11
	v_add_f32_e32 v4, v14, v4
	v_add_f32_e32 v5, v15, v5
	v_add_f32_e32 v6, v12, v6
	v_add_f32_e32 v7, v13, v7
	v_add_f32_e32 v8, v18, v8
	v_add_f32_e32 v9, v19, v9
	v_add_f32_e32 v10, v16, v10
	v_add_f32_e32 v11, v17, v11
	v_cvt_pk_bf16_f32 v4, v4, v5
	v_cvt_pk_bf16_f32 v5, v6, v7
	v_cvt_pk_bf16_f32 v6, v8, v9
	v_cvt_pk_bf16_f32 v7, v10, v11
	global_load_dwordx4 v[8:11], v[22:23], off offset:256
	v_pk_mul_f32 v[12:13], v[88:89], s[36:37] op_sel_hi:[1,0]
	v_pk_mul_f32 v[14:15], v[86:87], s[36:37] op_sel_hi:[1,0]
	v_pk_mul_f32 v[16:17], v[84:85], s[36:37] op_sel_hi:[1,0]
	v_pk_mul_f32 v[18:19], v[82:83], s[36:37] op_sel_hi:[1,0]
	global_store_dwordx4 v[20:21], v[4:7], off
	v_addc_co_u32_e32 v25, vcc, 0, v3, vcc
	v_lshl_add_u64 v[20:21], v[2:3], 0, s[40:41]
	s_waitcnt vmcnt(1)
	v_lshlrev_b32_e32 v4, 16, v8
	v_and_b32_e32 v5, 0xffff0000, v8
	v_lshlrev_b32_e32 v6, 16, v9
	v_and_b32_e32 v7, 0xffff0000, v9
	v_lshlrev_b32_e32 v8, 16, v10
	v_and_b32_e32 v9, 0xffff0000, v10
	v_lshlrev_b32_e32 v10, 16, v11
	v_and_b32_e32 v11, 0xffff0000, v11
	v_add_f32_e32 v4, v14, v4
	v_add_f32_e32 v5, v15, v5
	v_add_f32_e32 v6, v12, v6
	v_add_f32_e32 v7, v13, v7
	v_add_f32_e32 v8, v18, v8
	v_add_f32_e32 v9, v19, v9
	v_add_f32_e32 v10, v16, v10
	v_add_f32_e32 v11, v17, v11
	v_cvt_pk_bf16_f32 v4, v4, v5
	v_cvt_pk_bf16_f32 v5, v6, v7
	v_cvt_pk_bf16_f32 v6, v8, v9
	v_cvt_pk_bf16_f32 v7, v10, v11
	global_load_dwordx4 v[8:11], v[24:25], off
	v_pk_mul_f32 v[12:13], v[80:81], s[36:37] op_sel_hi:[1,0]
	v_pk_mul_f32 v[14:15], v[78:79], s[36:37] op_sel_hi:[1,0]
	v_pk_mul_f32 v[16:17], v[76:77], s[36:37] op_sel_hi:[1,0]
	v_pk_mul_f32 v[18:19], v[74:75], s[36:37] op_sel_hi:[1,0]
	global_store_dwordx4 v[22:23], v[4:7], off offset:256
	v_add_co_u32_e32 v22, vcc, s71, v2
	s_waitcnt vmcnt(1)
	v_lshlrev_b32_e32 v4, 16, v8
	v_and_b32_e32 v5, 0xffff0000, v8
	v_lshlrev_b32_e32 v6, 16, v9
	v_and_b32_e32 v7, 0xffff0000, v9
	v_lshlrev_b32_e32 v8, 16, v10
	v_and_b32_e32 v9, 0xffff0000, v10
	v_lshlrev_b32_e32 v10, 16, v11
	v_and_b32_e32 v11, 0xffff0000, v11
	v_add_f32_e32 v4, v14, v4
	v_add_f32_e32 v5, v15, v5
	v_add_f32_e32 v6, v12, v6
	v_add_f32_e32 v7, v13, v7
	v_add_f32_e32 v8, v18, v8
	v_add_f32_e32 v9, v19, v9
	v_add_f32_e32 v10, v16, v10
	v_add_f32_e32 v11, v17, v11
	v_cvt_pk_bf16_f32 v4, v4, v5
	v_cvt_pk_bf16_f32 v5, v6, v7
	v_cvt_pk_bf16_f32 v6, v8, v9
	v_cvt_pk_bf16_f32 v7, v10, v11
	global_load_dwordx4 v[8:11], v[20:21], off offset:256
	v_pk_mul_f32 v[12:13], v[72:73], s[36:37] op_sel_hi:[1,0]
	v_pk_mul_f32 v[14:15], v[70:71], s[36:37] op_sel_hi:[1,0]
	v_pk_mul_f32 v[16:17], v[68:69], s[36:37] op_sel_hi:[1,0]
	v_pk_mul_f32 v[18:19], v[66:67], s[36:37] op_sel_hi:[1,0]
	global_store_dwordx4 v[24:25], v[4:7], off
	v_addc_co_u32_e32 v23, vcc, 0, v3, vcc
	v_lshl_add_u64 v[24:25], v[2:3], 0, s[42:43]
	s_waitcnt vmcnt(1)
	v_lshlrev_b32_e32 v4, 16, v8
	v_and_b32_e32 v5, 0xffff0000, v8
	v_lshlrev_b32_e32 v6, 16, v9
	v_and_b32_e32 v7, 0xffff0000, v9
	v_lshlrev_b32_e32 v8, 16, v10
	v_and_b32_e32 v9, 0xffff0000, v10
	v_lshlrev_b32_e32 v10, 16, v11
	v_and_b32_e32 v11, 0xffff0000, v11
	v_add_f32_e32 v4, v14, v4
	v_add_f32_e32 v5, v15, v5
	v_add_f32_e32 v6, v12, v6
	v_add_f32_e32 v7, v13, v7
	v_add_f32_e32 v8, v18, v8
	v_add_f32_e32 v9, v19, v9
	v_add_f32_e32 v10, v16, v10
	v_add_f32_e32 v11, v17, v11
	v_cvt_pk_bf16_f32 v4, v4, v5
	v_cvt_pk_bf16_f32 v5, v6, v7
	v_cvt_pk_bf16_f32 v6, v8, v9
	v_cvt_pk_bf16_f32 v7, v10, v11
	global_load_dwordx4 v[8:11], v[22:23], off
	v_pk_mul_f32 v[12:13], v[64:65], s[36:37] op_sel_hi:[1,0]
	v_pk_mul_f32 v[14:15], v[62:63], s[36:37] op_sel_hi:[1,0]
	v_pk_mul_f32 v[16:17], v[60:61], s[36:37] op_sel_hi:[1,0]
	v_pk_mul_f32 v[18:19], v[58:59], s[36:37] op_sel_hi:[1,0]
	global_store_dwordx4 v[20:21], v[4:7], off offset:256
	v_add_co_u32_e32 v20, vcc, s72, v2
	s_waitcnt vmcnt(1)
	v_lshlrev_b32_e32 v4, 16, v8
	v_and_b32_e32 v5, 0xffff0000, v8
	v_lshlrev_b32_e32 v6, 16, v9
	v_and_b32_e32 v7, 0xffff0000, v9
	v_lshlrev_b32_e32 v8, 16, v10
	v_and_b32_e32 v9, 0xffff0000, v10
	v_lshlrev_b32_e32 v10, 16, v11
	v_and_b32_e32 v11, 0xffff0000, v11
	v_add_f32_e32 v4, v14, v4
	v_add_f32_e32 v5, v15, v5
	v_add_f32_e32 v6, v12, v6
	v_add_f32_e32 v7, v13, v7
	v_add_f32_e32 v8, v18, v8
	v_add_f32_e32 v9, v19, v9
	v_add_f32_e32 v10, v16, v10
	v_add_f32_e32 v11, v17, v11
	v_cvt_pk_bf16_f32 v4, v4, v5
	v_cvt_pk_bf16_f32 v5, v6, v7
	v_cvt_pk_bf16_f32 v6, v8, v9
	v_cvt_pk_bf16_f32 v7, v10, v11
	global_load_dwordx4 v[8:11], v[24:25], off offset:256
	v_pk_mul_f32 v[12:13], v[56:57], s[36:37] op_sel_hi:[1,0]
	v_pk_mul_f32 v[14:15], v[54:55], s[36:37] op_sel_hi:[1,0]
	v_pk_mul_f32 v[16:17], v[52:53], s[36:37] op_sel_hi:[1,0]
	v_pk_mul_f32 v[18:19], v[50:51], s[36:37] op_sel_hi:[1,0]
	global_store_dwordx4 v[22:23], v[4:7], off
	v_addc_co_u32_e32 v21, vcc, 0, v3, vcc
	v_lshl_add_u64 v[22:23], v[2:3], 0, s[44:45]
	s_andn2_b64 vcc, exec, s[4:5]
	s_mov_b64 s[4:5], -1
	s_waitcnt vmcnt(1)
	v_lshlrev_b32_e32 v4, 16, v8
	v_and_b32_e32 v5, 0xffff0000, v8
	v_lshlrev_b32_e32 v6, 16, v9
	v_and_b32_e32 v7, 0xffff0000, v9
	v_lshlrev_b32_e32 v8, 16, v10
	v_and_b32_e32 v9, 0xffff0000, v10
	v_lshlrev_b32_e32 v10, 16, v11
	v_and_b32_e32 v11, 0xffff0000, v11
	v_add_f32_e32 v4, v14, v4
	v_add_f32_e32 v5, v15, v5
	v_add_f32_e32 v6, v12, v6
	v_add_f32_e32 v7, v13, v7
	v_add_f32_e32 v8, v18, v8
	v_add_f32_e32 v9, v19, v9
	v_add_f32_e32 v10, v16, v10
	v_add_f32_e32 v11, v17, v11
	v_cvt_pk_bf16_f32 v4, v4, v5
	v_cvt_pk_bf16_f32 v5, v6, v7
	v_cvt_pk_bf16_f32 v6, v8, v9
	v_cvt_pk_bf16_f32 v7, v10, v11
	global_load_dwordx4 v[8:11], v[20:21], off
	v_pk_mul_f32 v[12:13], v[48:49], s[36:37] op_sel_hi:[1,0]
	v_pk_mul_f32 v[14:15], v[46:47], s[36:37] op_sel_hi:[1,0]
	v_pk_mul_f32 v[16:17], v[44:45], s[36:37] op_sel_hi:[1,0]
	v_pk_mul_f32 v[18:19], v[42:43], s[36:37] op_sel_hi:[1,0]
	global_store_dwordx4 v[24:25], v[4:7], off offset:256
	s_waitcnt vmcnt(1)
	v_lshlrev_b32_e32 v2, 16, v8
	v_and_b32_e32 v3, 0xffff0000, v8
	v_lshlrev_b32_e32 v4, 16, v9
	v_and_b32_e32 v5, 0xffff0000, v9
	v_lshlrev_b32_e32 v6, 16, v10
	v_and_b32_e32 v7, 0xffff0000, v10
	v_lshlrev_b32_e32 v8, 16, v11
	v_and_b32_e32 v9, 0xffff0000, v11
	v_add_f32_e32 v2, v14, v2
	v_add_f32_e32 v3, v15, v3
	v_add_f32_e32 v4, v12, v4
	v_add_f32_e32 v5, v13, v5
	v_add_f32_e32 v6, v18, v6
	v_add_f32_e32 v7, v19, v7
	v_add_f32_e32 v8, v16, v8
	v_add_f32_e32 v9, v17, v9
	v_cvt_pk_bf16_f32 v2, v2, v3
	v_cvt_pk_bf16_f32 v3, v4, v5
	v_cvt_pk_bf16_f32 v4, v6, v7
	v_cvt_pk_bf16_f32 v5, v8, v9
	global_load_dwordx4 v[6:9], v[22:23], off offset:256
	v_pk_mul_f32 v[10:11], v[40:41], s[36:37] op_sel_hi:[1,0]
	v_pk_mul_f32 v[12:13], v[38:39], s[36:37] op_sel_hi:[1,0]
	global_store_dwordx4 v[20:21], v[2:5], off
	v_pk_mul_f32 v[14:15], v[36:37], s[36:37] op_sel_hi:[1,0]
	v_pk_mul_f32 v[16:17], v[34:35], s[36:37] op_sel_hi:[1,0]
	s_waitcnt vmcnt(1)
	v_lshlrev_b32_e32 v2, 16, v6
	v_and_b32_e32 v3, 0xffff0000, v6
	v_lshlrev_b32_e32 v4, 16, v7
	v_and_b32_e32 v5, 0xffff0000, v7
	v_lshlrev_b32_e32 v6, 16, v8
	v_and_b32_e32 v7, 0xffff0000, v8
	v_lshlrev_b32_e32 v8, 16, v9
	v_and_b32_e32 v9, 0xffff0000, v9
	v_add_f32_e32 v2, v12, v2
	v_add_f32_e32 v3, v13, v3
	v_add_f32_e32 v4, v10, v4
	v_add_f32_e32 v5, v11, v5
	v_add_f32_e32 v6, v16, v6
	v_add_f32_e32 v7, v17, v7
	v_add_f32_e32 v8, v14, v8
	v_add_f32_e32 v9, v15, v9
	v_cvt_pk_bf16_f32 v2, v2, v3
	v_cvt_pk_bf16_f32 v3, v4, v5
	v_cvt_pk_bf16_f32 v4, v6, v7
	v_cvt_pk_bf16_f32 v5, v8, v9
	global_store_dwordx4 v[22:23], v[2:5], off offset:256
	s_cbranch_vccnz .LBB0_763
	s_andn2_b64 vcc, exec, s[12:13]
	s_cbranch_vccnz .LBB0_762
	s_branch .LBB0_762

.LBB0_906:
	v_lshl_add_u32 v8, s54, 8, v1
	v_lshl_or_b32 v2, s73, 8, v187
	v_ashrrev_i32_e32 v9, 31, v8
	v_ashrrev_i32_e32 v3, 31, v2
	v_lshlrev_b64 v[4:5], 12, v[8:9]
	v_lshl_add_u64 v[4:5], s[14:15], 0, v[4:5]
	v_lshlrev_b64 v[10:11], 1, v[2:3]
	v_lshl_add_u64 v[2:3], v[4:5], 0, v[10:11]
	v_pk_mul_f32 v[4:5], v[158:159], s[38:39] op_sel_hi:[1,0]
	v_pk_mul_f32 v[6:7], v[160:161], s[38:39] op_sel_hi:[1,0]
	v_cvt_pk_bf16_f32 v4, v4, v5
	v_pk_mul_f32 v[12:13], v[156:157], s[38:39] op_sel_hi:[1,0]
	v_cvt_pk_bf16_f32 v5, v6, v7
	v_pk_mul_f32 v[14:15], v[154:155], s[38:39] op_sel_hi:[1,0]
	v_pk_mul_f32 v[16:17], v[138:139], s[38:39] op_sel_hi:[1,0]
	v_cvt_pk_bf16_f32 v6, v14, v15
	v_cvt_pk_bf16_f32 v7, v12, v13
	global_store_dwordx4 v[2:3], v[4:7], off
	v_pk_mul_f32 v[12:13], v[148:149], s[38:39] op_sel_hi:[1,0]
	v_pk_mul_f32 v[14:15], v[146:147], s[38:39] op_sel_hi:[1,0]
	v_pk_mul_f32 v[4:5], v[150:151], s[38:39] op_sel_hi:[1,0]
	v_pk_mul_f32 v[6:7], v[152:153], s[38:39] op_sel_hi:[1,0]
	v_cvt_pk_bf16_f32 v4, v4, v5
	s_nop 0
	v_cvt_pk_bf16_f32 v5, v6, v7
	v_cvt_pk_bf16_f32 v6, v14, v15
	v_cvt_pk_bf16_f32 v7, v12, v13
	global_store_dwordx4 v[2:3], v[4:7], off offset:256
	v_pk_mul_f32 v[14:15], v[140:141], s[38:39] op_sel_hi:[1,0]
	s_nop 0
	v_or_b32_e32 v4, 16, v8
	v_ashrrev_i32_e32 v5, 31, v4
	v_lshlrev_b64 v[4:5], 12, v[4:5]
	v_lshl_add_u64 v[4:5], s[14:15], 0, v[4:5]
	v_lshl_add_u64 v[12:13], v[4:5], 0, v[10:11]
	v_pk_mul_f32 v[4:5], v[142:143], s[38:39] op_sel_hi:[1,0]
	v_pk_mul_f32 v[6:7], v[144:145], s[38:39] op_sel_hi:[1,0]
	v_cvt_pk_bf16_f32 v4, v4, v5
	s_nop 0
	v_cvt_pk_bf16_f32 v5, v6, v7
	v_cvt_pk_bf16_f32 v6, v16, v17
	v_cvt_pk_bf16_f32 v7, v14, v15
	global_store_dwordx4 v[12:13], v[4:7], off
	v_pk_mul_f32 v[14:15], v[132:133], s[38:39] op_sel_hi:[1,0]
	v_pk_mul_f32 v[16:17], v[130:131], s[38:39] op_sel_hi:[1,0]
	v_pk_mul_f32 v[4:5], v[134:135], s[38:39] op_sel_hi:[1,0]
	v_pk_mul_f32 v[6:7], v[136:137], s[38:39] op_sel_hi:[1,0]
	v_cvt_pk_bf16_f32 v4, v4, v5
	s_nop 0
	v_cvt_pk_bf16_f32 v5, v6, v7
	v_cvt_pk_bf16_f32 v6, v16, v17
	v_cvt_pk_bf16_f32 v7, v14, v15
	global_store_dwordx4 v[12:13], v[4:7], off offset:256
	v_pk_mul_f32 v[14:15], v[120:121], s[38:39] op_sel_hi:[1,0]
	v_pk_mul_f32 v[16:17], v[118:119], s[38:39] op_sel_hi:[1,0]
	v_or_b32_e32 v4, 32, v8
	v_ashrrev_i32_e32 v5, 31, v4
	v_lshlrev_b64 v[4:5], 12, v[4:5]
	v_lshl_add_u64 v[4:5], s[14:15], 0, v[4:5]
	v_lshl_add_u64 v[12:13], v[4:5], 0, v[10:11]
	v_pk_mul_f32 v[4:5], v[126:127], s[38:39] op_sel_hi:[1,0]
	v_pk_mul_f32 v[6:7], v[128:129], s[38:39] op_sel_hi:[1,0]
	v_cvt_pk_bf16_f32 v4, v4, v5
	s_nop 0
	v_cvt_pk_bf16_f32 v5, v6, v7
	v_cvt_pk_bf16_f32 v6, v16, v17
	v_cvt_pk_bf16_f32 v7, v14, v15
	global_store_dwordx4 v[12:13], v[4:7], off
	v_pk_mul_f32 v[14:15], v[108:109], s[38:39] op_sel_hi:[1,0]
	v_pk_mul_f32 v[16:17], v[106:107], s[38:39] op_sel_hi:[1,0]
	v_pk_mul_f32 v[4:5], v[110:111], s[38:39] op_sel_hi:[1,0]
	v_pk_mul_f32 v[6:7], v[112:113], s[38:39] op_sel_hi:[1,0]
	v_cvt_pk_bf16_f32 v4, v4, v5
	s_nop 0
	v_cvt_pk_bf16_f32 v5, v6, v7
	v_cvt_pk_bf16_f32 v6, v16, v17
	v_cvt_pk_bf16_f32 v7, v14, v15
	global_store_dwordx4 v[12:13], v[4:7], off offset:256
	v_pk_mul_f32 v[12:13], v[82:83], s[38:39] op_sel_hi:[1,0]
	s_nop 0
	v_or_b32_e32 v4, 48, v8
	v_ashrrev_i32_e32 v5, 31, v4
	v_lshlrev_b64 v[4:5], 12, v[4:5]
	v_lshl_add_u64 v[4:5], s[14:15], 0, v[4:5]
	v_lshl_add_u64 v[8:9], v[4:5], 0, v[10:11]
	v_pk_mul_f32 v[6:7], v[92:93], s[38:39] op_sel_hi:[1,0]
	v_pk_mul_f32 v[4:5], v[90:91], s[38:39] op_sel_hi:[1,0]
	v_pk_mul_f32 v[10:11], v[84:85], s[38:39] op_sel_hi:[1,0]
	v_cvt_pk_bf16_f32 v4, v4, v5
	v_cvt_pk_bf16_f32 v5, v6, v7
	v_cvt_pk_bf16_f32 v6, v12, v13
	v_pk_mul_f32 v[12:13], v[74:75], s[38:39] op_sel_hi:[1,0]
	v_cvt_pk_bf16_f32 v7, v10, v11
	global_store_dwordx4 v[8:9], v[4:7], off
	v_pk_mul_f32 v[10:11], v[76:77], s[38:39] op_sel_hi:[1,0]
	s_nop 0
	v_pk_mul_f32 v[6:7], v[80:81], s[38:39] op_sel_hi:[1,0]
	v_pk_mul_f32 v[4:5], v[78:79], s[38:39] op_sel_hi:[1,0]
	s_nop 0
	v_cvt_pk_bf16_f32 v4, v4, v5
	v_cvt_pk_bf16_f32 v5, v6, v7
	v_cvt_pk_bf16_f32 v6, v12, v13
	v_cvt_pk_bf16_f32 v7, v10, v11
	global_store_dwordx4 v[8:9], v[4:7], off offset:256
	v_pk_mul_f32 v[10:11], v[116:117], s[38:39] op_sel_hi:[1,0]
	v_pk_mul_f32 v[12:13], v[114:115], s[38:39] op_sel_hi:[1,0]
	v_pk_mul_f32 v[6:7], v[124:125], s[38:39] op_sel_hi:[1,0]
	v_pk_mul_f32 v[4:5], v[122:123], s[38:39] op_sel_hi:[1,0]
	v_lshl_add_u64 v[8:9], v[2:3], 0, s[6:7]
	v_cvt_pk_bf16_f32 v4, v4, v5
	v_cvt_pk_bf16_f32 v5, v6, v7
	v_cvt_pk_bf16_f32 v6, v12, v13
	v_cvt_pk_bf16_f32 v7, v10, v11
	v_add_co_u32_e32 v10, vcc, s69, v2
	v_pk_mul_f32 v[12:13], v[98:99], s[38:39] op_sel_hi:[1,0]
	s_nop 0
	v_addc_co_u32_e32 v11, vcc, 0, v3, vcc
	global_store_dwordx4 v[10:11], v[4:7], off
	v_pk_mul_f32 v[10:11], v[100:101], s[38:39] op_sel_hi:[1,0]
	s_nop 0
	v_pk_mul_f32 v[6:7], v[104:105], s[38:39] op_sel_hi:[1,0]
	v_pk_mul_f32 v[4:5], v[102:103], s[38:39] op_sel_hi:[1,0]
	s_nop 0
	v_cvt_pk_bf16_f32 v4, v4, v5
	v_cvt_pk_bf16_f32 v5, v6, v7
	v_cvt_pk_bf16_f32 v6, v12, v13
	v_cvt_pk_bf16_f32 v7, v10, v11
	global_store_dwordx4 v[8:9], v[4:7], off offset:256
	v_pk_mul_f32 v[10:11], v[88:89], s[38:39] op_sel_hi:[1,0]
	v_pk_mul_f32 v[12:13], v[86:87], s[38:39] op_sel_hi:[1,0]
	v_pk_mul_f32 v[6:7], v[96:97], s[38:39] op_sel_hi:[1,0]
	v_pk_mul_f32 v[4:5], v[94:95], s[38:39] op_sel_hi:[1,0]
	v_lshl_add_u64 v[8:9], v[2:3], 0, s[40:41]
	v_cvt_pk_bf16_f32 v4, v4, v5
	v_cvt_pk_bf16_f32 v5, v6, v7
	v_cvt_pk_bf16_f32 v6, v12, v13
	v_cvt_pk_bf16_f32 v7, v10, v11
	v_add_co_u32_e32 v10, vcc, s70, v2
	v_pk_mul_f32 v[12:13], v[66:67], s[38:39] op_sel_hi:[1,0]
	s_nop 0
	v_addc_co_u32_e32 v11, vcc, 0, v3, vcc
	global_store_dwordx4 v[10:11], v[4:7], off
	v_pk_mul_f32 v[10:11], v[68:69], s[38:39] op_sel_hi:[1,0]
	s_nop 0
	v_pk_mul_f32 v[6:7], v[72:73], s[38:39] op_sel_hi:[1,0]
	v_pk_mul_f32 v[4:5], v[70:71], s[38:39] op_sel_hi:[1,0]
	s_nop 0
	v_cvt_pk_bf16_f32 v4, v4, v5
	v_cvt_pk_bf16_f32 v5, v6, v7
	v_cvt_pk_bf16_f32 v6, v12, v13
	v_cvt_pk_bf16_f32 v7, v10, v11
	global_store_dwordx4 v[8:9], v[4:7], off offset:256
	v_pk_mul_f32 v[10:11], v[60:61], s[38:39] op_sel_hi:[1,0]
	v_pk_mul_f32 v[12:13], v[58:59], s[38:39] op_sel_hi:[1,0]
	v_pk_mul_f32 v[6:7], v[64:65], s[38:39] op_sel_hi:[1,0]
	v_pk_mul_f32 v[4:5], v[62:63], s[38:39] op_sel_hi:[1,0]
	v_lshl_add_u64 v[8:9], v[2:3], 0, s[42:43]
	v_cvt_pk_bf16_f32 v4, v4, v5
	v_cvt_pk_bf16_f32 v5, v6, v7
	v_cvt_pk_bf16_f32 v6, v12, v13
	v_cvt_pk_bf16_f32 v7, v10, v11
	v_add_co_u32_e32 v10, vcc, s71, v2
	v_pk_mul_f32 v[12:13], v[50:51], s[38:39] op_sel_hi:[1,0]
	s_nop 0
	v_addc_co_u32_e32 v11, vcc, 0, v3, vcc
	global_store_dwordx4 v[10:11], v[4:7], off
	v_pk_mul_f32 v[10:11], v[52:53], s[38:39] op_sel_hi:[1,0]
	s_nop 0
	v_pk_mul_f32 v[4:5], v[54:55], s[38:39] op_sel_hi:[1,0]
	v_pk_mul_f32 v[6:7], v[56:57], s[38:39] op_sel_hi:[1,0]
	v_cvt_pk_bf16_f32 v4, v4, v5
	s_nop 0
	v_cvt_pk_bf16_f32 v5, v6, v7
	v_cvt_pk_bf16_f32 v6, v12, v13
	v_cvt_pk_bf16_f32 v7, v10, v11
	global_store_dwordx4 v[8:9], v[4:7], off offset:256
	v_lshl_add_u64 v[8:9], v[2:3], 0, s[44:45]
	v_add_co_u32_e32 v2, vcc, s72, v2
	v_pk_mul_f32 v[4:5], v[46:47], s[38:39] op_sel_hi:[1,0]
	v_pk_mul_f32 v[6:7], v[48:49], s[38:39] op_sel_hi:[1,0]
	v_cvt_pk_bf16_f32 v4, v4, v5
	v_addc_co_u32_e32 v3, vcc, 0, v3, vcc
	v_cvt_pk_bf16_f32 v5, v6, v7
	v_pk_mul_f32 v[10:11], v[44:45], s[38:39] op_sel_hi:[1,0]
	v_pk_mul_f32 v[12:13], v[42:43], s[38:39] op_sel_hi:[1,0]
	s_andn2_b64 vcc, exec, s[4:5]
	v_cvt_pk_bf16_f32 v6, v12, v13
	v_cvt_pk_bf16_f32 v7, v10, v11
	global_store_dwordx4 v[2:3], v[4:7], off
	v_pk_mul_f32 v[2:3], v[38:39], s[38:39] op_sel_hi:[1,0]
	s_mov_b64 s[4:5], -1
	v_pk_mul_f32 v[4:5], v[40:41], s[38:39] op_sel_hi:[1,0]
	v_pk_mul_f32 v[6:7], v[36:37], s[38:39] op_sel_hi:[1,0]
	v_pk_mul_f32 v[10:11], v[34:35], s[38:39] op_sel_hi:[1,0]
	v_cvt_pk_bf16_f32 v2, v2, v3
	v_cvt_pk_bf16_f32 v3, v4, v5
	s_nop 0
	v_cvt_pk_bf16_f32 v4, v10, v11
	v_cvt_pk_bf16_f32 v5, v6, v7
	global_store_dwordx4 v[8:9], v[2:5], off offset:256
	s_cbranch_vccnz .LBB0_899
	s_andn2_b64 vcc, exec, s[12:13]
	s_cbranch_vccnz .LBB0_898
	s_branch .LBB0_898
.LBB0_909:
	s_waitcnt vmcnt(0)
	v_readlane_b32 s80, v255, 5
	s_cmp_lg_u64 s[30:31], 0
	s_cbranch_scc0 .Lmy_na_5
	s_barrier

.LBB0_1037:
	v_lshl_add_u32 v8, s54, 8, v1
	v_lshl_or_b32 v2, s74, 8, v187
	v_ashrrev_i32_e32 v9, 31, v8
	v_ashrrev_i32_e32 v3, 31, v2
	v_lshlrev_b64 v[4:5], 13, v[8:9]
	v_lshl_add_u64 v[4:5], s[12:13], 0, v[4:5]
	v_lshlrev_b64 v[10:11], 1, v[2:3]
	v_lshl_add_u64 v[2:3], v[4:5], 0, v[10:11]
	v_pk_mul_f32 v[4:5], v[158:159], s[36:37] op_sel_hi:[1,0]
	v_pk_mul_f32 v[6:7], v[160:161], s[36:37] op_sel_hi:[1,0]
	v_cvt_pk_bf16_f32 v4, v4, v5
	v_pk_mul_f32 v[12:13], v[156:157], s[36:37] op_sel_hi:[1,0]
	v_cvt_pk_bf16_f32 v5, v6, v7
	v_pk_mul_f32 v[14:15], v[154:155], s[36:37] op_sel_hi:[1,0]
	v_pk_mul_f32 v[16:17], v[138:139], s[36:37] op_sel_hi:[1,0]
	v_cvt_pk_bf16_f32 v6, v14, v15
	v_cvt_pk_bf16_f32 v7, v12, v13
	global_store_dwordx4 v[2:3], v[4:7], off
	v_pk_mul_f32 v[12:13], v[148:149], s[36:37] op_sel_hi:[1,0]
	v_pk_mul_f32 v[14:15], v[146:147], s[36:37] op_sel_hi:[1,0]
	v_pk_mul_f32 v[4:5], v[150:151], s[36:37] op_sel_hi:[1,0]
	v_pk_mul_f32 v[6:7], v[152:153], s[36:37] op_sel_hi:[1,0]
	v_cvt_pk_bf16_f32 v4, v4, v5
	s_nop 0
	v_cvt_pk_bf16_f32 v5, v6, v7
	v_cvt_pk_bf16_f32 v6, v14, v15
	v_cvt_pk_bf16_f32 v7, v12, v13
	global_store_dwordx4 v[2:3], v[4:7], off offset:256
	v_pk_mul_f32 v[14:15], v[140:141], s[36:37] op_sel_hi:[1,0]
	s_nop 0
	v_or_b32_e32 v4, 16, v8
	v_ashrrev_i32_e32 v5, 31, v4
	v_lshlrev_b64 v[4:5], 13, v[4:5]
	v_lshl_add_u64 v[4:5], s[12:13], 0, v[4:5]
	v_lshl_add_u64 v[12:13], v[4:5], 0, v[10:11]
	v_pk_mul_f32 v[4:5], v[142:143], s[36:37] op_sel_hi:[1,0]
	v_pk_mul_f32 v[6:7], v[144:145], s[36:37] op_sel_hi:[1,0]
	v_cvt_pk_bf16_f32 v4, v4, v5
	s_nop 0
	v_cvt_pk_bf16_f32 v5, v6, v7
	v_cvt_pk_bf16_f32 v6, v16, v17
	v_cvt_pk_bf16_f32 v7, v14, v15
	global_store_dwordx4 v[12:13], v[4:7], off
	v_pk_mul_f32 v[14:15], v[132:133], s[36:37] op_sel_hi:[1,0]
	v_pk_mul_f32 v[16:17], v[130:131], s[36:37] op_sel_hi:[1,0]
	v_pk_mul_f32 v[4:5], v[134:135], s[36:37] op_sel_hi:[1,0]
	v_pk_mul_f32 v[6:7], v[136:137], s[36:37] op_sel_hi:[1,0]
	v_cvt_pk_bf16_f32 v4, v4, v5
	s_nop 0
	v_cvt_pk_bf16_f32 v5, v6, v7
	v_cvt_pk_bf16_f32 v6, v16, v17
	v_cvt_pk_bf16_f32 v7, v14, v15
	global_store_dwordx4 v[12:13], v[4:7], off offset:256
	v_pk_mul_f32 v[14:15], v[120:121], s[36:37] op_sel_hi:[1,0]
	v_pk_mul_f32 v[16:17], v[118:119], s[36:37] op_sel_hi:[1,0]
	v_or_b32_e32 v4, 32, v8
	v_ashrrev_i32_e32 v5, 31, v4
	v_lshlrev_b64 v[4:5], 13, v[4:5]
	v_lshl_add_u64 v[4:5], s[12:13], 0, v[4:5]
	v_lshl_add_u64 v[12:13], v[4:5], 0, v[10:11]
	v_pk_mul_f32 v[4:5], v[126:127], s[36:37] op_sel_hi:[1,0]
	v_pk_mul_f32 v[6:7], v[128:129], s[36:37] op_sel_hi:[1,0]
	v_cvt_pk_bf16_f32 v4, v4, v5
	s_nop 0
	v_cvt_pk_bf16_f32 v5, v6, v7
	v_cvt_pk_bf16_f32 v6, v16, v17
	v_cvt_pk_bf16_f32 v7, v14, v15
	global_store_dwordx4 v[12:13], v[4:7], off
	v_pk_mul_f32 v[14:15], v[108:109], s[36:37] op_sel_hi:[1,0]
	v_pk_mul_f32 v[16:17], v[106:107], s[36:37] op_sel_hi:[1,0]
	v_pk_mul_f32 v[4:5], v[110:111], s[36:37] op_sel_hi:[1,0]
	v_pk_mul_f32 v[6:7], v[112:113], s[36:37] op_sel_hi:[1,0]
	v_cvt_pk_bf16_f32 v4, v4, v5
	s_nop 0
	v_cvt_pk_bf16_f32 v5, v6, v7
	v_cvt_pk_bf16_f32 v6, v16, v17
	v_cvt_pk_bf16_f32 v7, v14, v15
	global_store_dwordx4 v[12:13], v[4:7], off offset:256
	v_pk_mul_f32 v[12:13], v[82:83], s[36:37] op_sel_hi:[1,0]
	s_nop 0
	v_or_b32_e32 v4, 48, v8
	v_ashrrev_i32_e32 v5, 31, v4
	v_lshlrev_b64 v[4:5], 13, v[4:5]
	v_lshl_add_u64 v[4:5], s[12:13], 0, v[4:5]
	v_lshl_add_u64 v[8:9], v[4:5], 0, v[10:11]
	v_pk_mul_f32 v[6:7], v[92:93], s[36:37] op_sel_hi:[1,0]
	v_pk_mul_f32 v[4:5], v[90:91], s[36:37] op_sel_hi:[1,0]
	v_pk_mul_f32 v[10:11], v[84:85], s[36:37] op_sel_hi:[1,0]
	v_cvt_pk_bf16_f32 v4, v4, v5
	v_cvt_pk_bf16_f32 v5, v6, v7
	v_cvt_pk_bf16_f32 v6, v12, v13
	v_pk_mul_f32 v[12:13], v[74:75], s[36:37] op_sel_hi:[1,0]
	v_cvt_pk_bf16_f32 v7, v10, v11
	global_store_dwordx4 v[8:9], v[4:7], off
	v_pk_mul_f32 v[10:11], v[76:77], s[36:37] op_sel_hi:[1,0]
	s_nop 0
	v_pk_mul_f32 v[6:7], v[80:81], s[36:37] op_sel_hi:[1,0]
	v_pk_mul_f32 v[4:5], v[78:79], s[36:37] op_sel_hi:[1,0]
	s_nop 0
	v_cvt_pk_bf16_f32 v4, v4, v5
	v_cvt_pk_bf16_f32 v5, v6, v7
	v_cvt_pk_bf16_f32 v6, v12, v13
	v_cvt_pk_bf16_f32 v7, v10, v11
	global_store_dwordx4 v[8:9], v[4:7], off offset:256
	v_pk_mul_f32 v[10:11], v[116:117], s[36:37] op_sel_hi:[1,0]
	v_pk_mul_f32 v[12:13], v[114:115], s[36:37] op_sel_hi:[1,0]
	v_pk_mul_f32 v[6:7], v[124:125], s[36:37] op_sel_hi:[1,0]
	v_pk_mul_f32 v[4:5], v[122:123], s[36:37] op_sel_hi:[1,0]
	v_lshl_add_u64 v[8:9], v[2:3], 0, s[38:39]
	v_cvt_pk_bf16_f32 v4, v4, v5
	v_cvt_pk_bf16_f32 v5, v6, v7
	v_cvt_pk_bf16_f32 v6, v12, v13
	v_cvt_pk_bf16_f32 v7, v10, v11
	v_add_co_u32_e32 v10, vcc, s70, v2
	v_pk_mul_f32 v[12:13], v[98:99], s[36:37] op_sel_hi:[1,0]
	s_nop 0
	v_addc_co_u32_e32 v11, vcc, 0, v3, vcc
	global_store_dwordx4 v[10:11], v[4:7], off
	v_pk_mul_f32 v[10:11], v[100:101], s[36:37] op_sel_hi:[1,0]
	s_nop 0
	v_pk_mul_f32 v[6:7], v[104:105], s[36:37] op_sel_hi:[1,0]
	v_pk_mul_f32 v[4:5], v[102:103], s[36:37] op_sel_hi:[1,0]
	s_nop 0
	v_cvt_pk_bf16_f32 v4, v4, v5
	v_cvt_pk_bf16_f32 v5, v6, v7
	v_cvt_pk_bf16_f32 v6, v12, v13
	v_cvt_pk_bf16_f32 v7, v10, v11
	global_store_dwordx4 v[8:9], v[4:7], off offset:256
	v_pk_mul_f32 v[10:11], v[88:89], s[36:37] op_sel_hi:[1,0]
	v_pk_mul_f32 v[12:13], v[86:87], s[36:37] op_sel_hi:[1,0]
	v_pk_mul_f32 v[6:7], v[96:97], s[36:37] op_sel_hi:[1,0]
	v_pk_mul_f32 v[4:5], v[94:95], s[36:37] op_sel_hi:[1,0]
	v_lshl_add_u64 v[8:9], v[2:3], 0, s[40:41]
	v_cvt_pk_bf16_f32 v4, v4, v5
	v_cvt_pk_bf16_f32 v5, v6, v7
	v_cvt_pk_bf16_f32 v6, v12, v13
	v_cvt_pk_bf16_f32 v7, v10, v11
	v_add_co_u32_e32 v10, vcc, s71, v2
	v_pk_mul_f32 v[12:13], v[66:67], s[36:37] op_sel_hi:[1,0]
	s_nop 0
	v_addc_co_u32_e32 v11, vcc, 0, v3, vcc
	global_store_dwordx4 v[10:11], v[4:7], off
	v_pk_mul_f32 v[10:11], v[68:69], s[36:37] op_sel_hi:[1,0]
	s_nop 0
	v_pk_mul_f32 v[6:7], v[72:73], s[36:37] op_sel_hi:[1,0]
	v_pk_mul_f32 v[4:5], v[70:71], s[36:37] op_sel_hi:[1,0]
	s_nop 0
	v_cvt_pk_bf16_f32 v4, v4, v5
	v_cvt_pk_bf16_f32 v5, v6, v7
	v_cvt_pk_bf16_f32 v6, v12, v13
	v_cvt_pk_bf16_f32 v7, v10, v11
	global_store_dwordx4 v[8:9], v[4:7], off offset:256
	v_pk_mul_f32 v[10:11], v[60:61], s[36:37] op_sel_hi:[1,0]
	v_pk_mul_f32 v[12:13], v[58:59], s[36:37] op_sel_hi:[1,0]
	v_pk_mul_f32 v[6:7], v[64:65], s[36:37] op_sel_hi:[1,0]
	v_pk_mul_f32 v[4:5], v[62:63], s[36:37] op_sel_hi:[1,0]
	v_lshl_add_u64 v[8:9], v[2:3], 0, s[42:43]
	v_cvt_pk_bf16_f32 v4, v4, v5
	v_cvt_pk_bf16_f32 v5, v6, v7
	v_cvt_pk_bf16_f32 v6, v12, v13
	v_cvt_pk_bf16_f32 v7, v10, v11
	v_add_co_u32_e32 v10, vcc, s72, v2
	v_pk_mul_f32 v[12:13], v[50:51], s[36:37] op_sel_hi:[1,0]
	s_nop 0
	v_addc_co_u32_e32 v11, vcc, 0, v3, vcc
	global_store_dwordx4 v[10:11], v[4:7], off
	v_pk_mul_f32 v[10:11], v[52:53], s[36:37] op_sel_hi:[1,0]
	s_nop 0
	v_pk_mul_f32 v[4:5], v[54:55], s[36:37] op_sel_hi:[1,0]
	v_pk_mul_f32 v[6:7], v[56:57], s[36:37] op_sel_hi:[1,0]
	v_cvt_pk_bf16_f32 v4, v4, v5
	s_nop 0
	v_cvt_pk_bf16_f32 v5, v6, v7
	v_cvt_pk_bf16_f32 v6, v12, v13
	v_cvt_pk_bf16_f32 v7, v10, v11
	global_store_dwordx4 v[8:9], v[4:7], off offset:256
	v_lshl_add_u64 v[8:9], v[2:3], 0, s[44:45]
	v_add_co_u32_e32 v2, vcc, s73, v2
	v_pk_mul_f32 v[4:5], v[46:47], s[36:37] op_sel_hi:[1,0]
	v_pk_mul_f32 v[6:7], v[48:49], s[36:37] op_sel_hi:[1,0]
	v_cvt_pk_bf16_f32 v4, v4, v5
	v_addc_co_u32_e32 v3, vcc, 0, v3, vcc
	v_cvt_pk_bf16_f32 v5, v6, v7
	v_pk_mul_f32 v[10:11], v[44:45], s[36:37] op_sel_hi:[1,0]
	v_pk_mul_f32 v[12:13], v[42:43], s[36:37] op_sel_hi:[1,0]
	s_andn2_b64 vcc, exec, s[4:5]
	v_cvt_pk_bf16_f32 v6, v12, v13
	v_cvt_pk_bf16_f32 v7, v10, v11
	global_store_dwordx4 v[2:3], v[4:7], off
	v_pk_mul_f32 v[2:3], v[38:39], s[36:37] op_sel_hi:[1,0]
	s_mov_b64 s[4:5], -1
	v_pk_mul_f32 v[4:5], v[40:41], s[36:37] op_sel_hi:[1,0]
	v_pk_mul_f32 v[6:7], v[36:37], s[36:37] op_sel_hi:[1,0]
	v_pk_mul_f32 v[10:11], v[34:35], s[36:37] op_sel_hi:[1,0]
	v_cvt_pk_bf16_f32 v2, v2, v3
	v_cvt_pk_bf16_f32 v3, v4, v5
	s_nop 0
	v_cvt_pk_bf16_f32 v4, v10, v11
	v_cvt_pk_bf16_f32 v5, v6, v7
	global_store_dwordx4 v[8:9], v[2:5], off offset:256
	s_cbranch_vccnz .LBB0_1030
	s_andn2_b64 vcc, exec, s[6:7]
	s_cbranch_vccnz .LBB0_1029
	s_branch .LBB0_1029

.LBB0_1177:
	v_lshl_add_u32 v142, s48, 8, v1
	v_lshl_or_b32 v144, s70, 8, v254
	v_ashrrev_i32_e32 v143, 31, v142
	v_ashrrev_i32_e32 v145, 31, v144
	v_lshlrev_b64 v[146:147], 15, v[142:143]
	v_lshl_add_u64 v[146:147], s[8:9], 0, v[146:147]
	v_lshlrev_b64 v[144:145], 1, v[144:145]
	v_lshl_add_u64 v[146:147], v[146:147], 0, v[144:145]
	v_cvt_pk_bf16_f32 v122, v122, v123
	v_cvt_pk_bf16_f32 v123, v124, v125
	v_cvt_pk_bf16_f32 v124, v114, v115
	v_cvt_pk_bf16_f32 v125, v116, v117
	global_store_dwordx4 v[146:147], v[122:125], off
	v_cvt_pk_bf16_f32 v114, v126, v127
	v_cvt_pk_bf16_f32 v115, v128, v129
	v_cvt_pk_bf16_f32 v116, v118, v119
	v_cvt_pk_bf16_f32 v117, v120, v121
	global_store_dwordx4 v[146:147], v[114:117], off offset:256
	v_cvt_pk_bf16_f32 v106, v106, v107
	v_cvt_pk_bf16_f32 v107, v108, v109
	v_cvt_pk_bf16_f32 v108, v98, v99
	v_cvt_pk_bf16_f32 v109, v100, v101
	s_nop 1
	v_or_b32_e32 v114, 16, v142
	v_ashrrev_i32_e32 v115, 31, v114
	v_lshlrev_b64 v[114:115], 15, v[114:115]
	v_lshl_add_u64 v[114:115], s[8:9], 0, v[114:115]
	v_lshl_add_u64 v[114:115], v[114:115], 0, v[144:145]
	global_store_dwordx4 v[114:115], v[106:109], off
	v_cvt_pk_bf16_f32 v98, v110, v111
	v_cvt_pk_bf16_f32 v99, v112, v113
	v_cvt_pk_bf16_f32 v100, v102, v103
	v_cvt_pk_bf16_f32 v101, v104, v105
	global_store_dwordx4 v[114:115], v[98:101], off offset:256
	v_cvt_pk_bf16_f32 v90, v90, v91
	v_cvt_pk_bf16_f32 v91, v92, v93
	v_cvt_pk_bf16_f32 v92, v82, v83
	v_cvt_pk_bf16_f32 v93, v84, v85
	s_nop 1
	v_or_b32_e32 v98, 32, v142
	v_ashrrev_i32_e32 v99, 31, v98
	v_lshlrev_b64 v[98:99], 15, v[98:99]
	v_lshl_add_u64 v[98:99], s[8:9], 0, v[98:99]
	v_lshl_add_u64 v[98:99], v[98:99], 0, v[144:145]
	global_store_dwordx4 v[98:99], v[90:93], off
	v_cvt_pk_bf16_f32 v82, v94, v95
	v_cvt_pk_bf16_f32 v83, v96, v97
	v_cvt_pk_bf16_f32 v84, v86, v87
	v_cvt_pk_bf16_f32 v85, v88, v89
	global_store_dwordx4 v[98:99], v[82:85], off offset:256
	v_cvt_pk_bf16_f32 v58, v58, v59
	v_cvt_pk_bf16_f32 v59, v60, v61
	v_cvt_pk_bf16_f32 v60, v50, v51
	v_cvt_pk_bf16_f32 v61, v52, v53
	s_nop 1
	v_or_b32_e32 v82, 48, v142
	v_ashrrev_i32_e32 v83, 31, v82
	v_lshlrev_b64 v[82:83], 15, v[82:83]
	v_lshl_add_u64 v[82:83], s[8:9], 0, v[82:83]
	v_lshl_add_u64 v[82:83], v[82:83], 0, v[144:145]
	global_store_dwordx4 v[82:83], v[58:61], off
	v_cvt_pk_bf16_f32 v50, v62, v63
	v_cvt_pk_bf16_f32 v51, v64, v65
	v_cvt_pk_bf16_f32 v52, v54, v55
	v_cvt_pk_bf16_f32 v53, v56, v57
	v_add_co_u32_e32 v56, vcc, s66, v146
	global_store_dwordx4 v[82:83], v[50:53], off offset:256
	v_lshl_add_u64 v[54:55], v[146:147], 0, s[30:31]
	v_addc_co_u32_e32 v57, vcc, 0, v147, vcc
	v_cvt_pk_bf16_f32 v50, v78, v79
	v_cvt_pk_bf16_f32 v51, v80, v81
	v_cvt_pk_bf16_f32 v52, v70, v71
	v_cvt_pk_bf16_f32 v53, v72, v73
	global_store_dwordx4 v[56:57], v[50:53], off
	s_nop 1
	v_cvt_pk_bf16_f32 v50, v74, v75
	v_cvt_pk_bf16_f32 v51, v76, v77
	v_cvt_pk_bf16_f32 v52, v66, v67
	v_cvt_pk_bf16_f32 v53, v68, v69
	global_store_dwordx4 v[54:55], v[50:53], off offset:256
	v_cvt_pk_bf16_f32 v46, v46, v47
	v_cvt_pk_bf16_f32 v47, v48, v49
	v_cvt_pk_bf16_f32 v48, v38, v39
	v_add_co_u32_e32 v38, vcc, s67, v146
	s_nop 0
	v_lshl_add_u64 v[50:51], v[146:147], 0, s[34:35]
	v_addc_co_u32_e32 v39, vcc, 0, v147, vcc
	v_cvt_pk_bf16_f32 v49, v40, v41
	global_store_dwordx4 v[38:39], v[46:49], off
	v_cvt_pk_bf16_f32 v38, v42, v43
	v_cvt_pk_bf16_f32 v39, v44, v45
	v_cvt_pk_bf16_f32 v40, v34, v35
	v_cvt_pk_bf16_f32 v41, v36, v37
	global_store_dwordx4 v[50:51], v[38:41], off offset:256
	v_cvt_pk_bf16_f32 v30, v30, v31
	v_cvt_pk_bf16_f32 v31, v32, v33
	v_cvt_pk_bf16_f32 v32, v22, v23
	v_add_co_u32_e32 v22, vcc, s68, v146
	v_lshl_add_u64 v[34:35], v[146:147], 0, s[36:37]
	s_nop 0
	v_addc_co_u32_e32 v23, vcc, 0, v147, vcc
	v_cvt_pk_bf16_f32 v33, v24, v25
	global_store_dwordx4 v[22:23], v[30:33], off
	v_cvt_pk_bf16_f32 v22, v26, v27
	v_cvt_pk_bf16_f32 v23, v28, v29
	v_cvt_pk_bf16_f32 v24, v18, v19
	v_cvt_pk_bf16_f32 v25, v20, v21
	global_store_dwordx4 v[34:35], v[22:25], off offset:256
	v_cvt_pk_bf16_f32 v14, v14, v15
	v_cvt_pk_bf16_f32 v15, v16, v17
	v_cvt_pk_bf16_f32 v16, v6, v7
	v_add_co_u32_e32 v6, vcc, s69, v146
	v_lshl_add_u64 v[18:19], v[146:147], 0, s[38:39]
	s_nop 0
	v_addc_co_u32_e32 v7, vcc, 0, v147, vcc
	s_andn2_b64 vcc, exec, s[4:5]
	s_mov_b64 s[4:5], -1
	v_cvt_pk_bf16_f32 v17, v8, v9
	global_store_dwordx4 v[6:7], v[14:17], off
	v_cvt_pk_bf16_f32 v6, v10, v11
	v_cvt_pk_bf16_f32 v7, v12, v13
	v_cvt_pk_bf16_f32 v8, v2, v3
	v_cvt_pk_bf16_f32 v9, v4, v5
	global_store_dwordx4 v[18:19], v[6:9], off offset:256
	s_cbranch_vccnz .LBB0_1166
	s_andn2_b64 vcc, exec, s[6:7]
	s_cbranch_vccnz .LBB0_1165
	s_branch .LBB0_1165
.LBB0_1180:
	s_waitcnt vmcnt(0)
	v_readlane_b32 s80, v255, 5
	s_cmp_lg_u64 s[12:13], 0
	s_cbranch_scc0 .Lmy_na_7
	s_barrier

.LBB0_1331:
	v_lshl_add_u32 v142, s48, 8, v1
	v_lshl_or_b32 v144, s70, 8, v254
	v_ashrrev_i32_e32 v143, 31, v142
	v_ashrrev_i32_e32 v145, 31, v144
	v_lshlrev_b64 v[146:147], 13, v[142:143]
	v_lshl_add_u64 v[146:147], s[10:11], 0, v[146:147]
	v_lshlrev_b64 v[144:145], 1, v[144:145]
	v_lshl_add_u64 v[146:147], v[146:147], 0, v[144:145]
	v_cvt_pk_bf16_f32 v122, v122, v123
	v_cvt_pk_bf16_f32 v123, v124, v125
	v_cvt_pk_bf16_f32 v124, v114, v115
	v_cvt_pk_bf16_f32 v125, v116, v117
	global_store_dwordx4 v[146:147], v[122:125], off
	v_cvt_pk_bf16_f32 v114, v126, v127
	v_cvt_pk_bf16_f32 v115, v128, v129
	v_cvt_pk_bf16_f32 v116, v118, v119
	v_cvt_pk_bf16_f32 v117, v120, v121
	global_store_dwordx4 v[146:147], v[114:117], off offset:256
	v_cvt_pk_bf16_f32 v106, v106, v107
	v_cvt_pk_bf16_f32 v107, v108, v109
	v_cvt_pk_bf16_f32 v108, v98, v99
	v_cvt_pk_bf16_f32 v109, v100, v101
	s_nop 1
	v_or_b32_e32 v114, 16, v142
	v_ashrrev_i32_e32 v115, 31, v114
	v_lshlrev_b64 v[114:115], 13, v[114:115]
	v_lshl_add_u64 v[114:115], s[10:11], 0, v[114:115]
	v_lshl_add_u64 v[114:115], v[114:115], 0, v[144:145]
	global_store_dwordx4 v[114:115], v[106:109], off
	v_cvt_pk_bf16_f32 v98, v110, v111
	v_cvt_pk_bf16_f32 v99, v112, v113
	v_cvt_pk_bf16_f32 v100, v102, v103
	v_cvt_pk_bf16_f32 v101, v104, v105
	global_store_dwordx4 v[114:115], v[98:101], off offset:256
	v_cvt_pk_bf16_f32 v90, v90, v91
	v_cvt_pk_bf16_f32 v91, v92, v93
	v_cvt_pk_bf16_f32 v92, v82, v83
	v_cvt_pk_bf16_f32 v93, v84, v85
	s_nop 1
	v_or_b32_e32 v98, 32, v142
	v_ashrrev_i32_e32 v99, 31, v98
	v_lshlrev_b64 v[98:99], 13, v[98:99]
	v_lshl_add_u64 v[98:99], s[10:11], 0, v[98:99]
	v_lshl_add_u64 v[98:99], v[98:99], 0, v[144:145]
	global_store_dwordx4 v[98:99], v[90:93], off
	v_cvt_pk_bf16_f32 v82, v94, v95
	v_cvt_pk_bf16_f32 v83, v96, v97
	v_cvt_pk_bf16_f32 v84, v86, v87
	v_cvt_pk_bf16_f32 v85, v88, v89
	global_store_dwordx4 v[98:99], v[82:85], off offset:256
	v_cvt_pk_bf16_f32 v58, v58, v59
	v_cvt_pk_bf16_f32 v59, v60, v61
	v_cvt_pk_bf16_f32 v60, v50, v51
	v_cvt_pk_bf16_f32 v61, v52, v53
	s_nop 1
	v_or_b32_e32 v82, 48, v142
	v_ashrrev_i32_e32 v83, 31, v82
	v_lshlrev_b64 v[82:83], 13, v[82:83]
	v_lshl_add_u64 v[82:83], s[10:11], 0, v[82:83]
	v_lshl_add_u64 v[82:83], v[82:83], 0, v[144:145]
	global_store_dwordx4 v[82:83], v[58:61], off
	v_cvt_pk_bf16_f32 v50, v62, v63
	v_cvt_pk_bf16_f32 v51, v64, v65
	v_cvt_pk_bf16_f32 v52, v54, v55
	v_cvt_pk_bf16_f32 v53, v56, v57
	v_add_co_u32_e32 v56, vcc, s66, v146
	global_store_dwordx4 v[82:83], v[50:53], off offset:256
	v_lshl_add_u64 v[54:55], v[146:147], 0, s[6:7]
	v_addc_co_u32_e32 v57, vcc, 0, v147, vcc
	v_cvt_pk_bf16_f32 v50, v78, v79
	v_cvt_pk_bf16_f32 v51, v80, v81
	v_cvt_pk_bf16_f32 v52, v70, v71
	v_cvt_pk_bf16_f32 v53, v72, v73
	global_store_dwordx4 v[56:57], v[50:53], off
	s_nop 1
	v_cvt_pk_bf16_f32 v50, v74, v75
	v_cvt_pk_bf16_f32 v51, v76, v77
	v_cvt_pk_bf16_f32 v52, v66, v67
	v_cvt_pk_bf16_f32 v53, v68, v69
	global_store_dwordx4 v[54:55], v[50:53], off offset:256
	v_cvt_pk_bf16_f32 v46, v46, v47
	v_cvt_pk_bf16_f32 v47, v48, v49
	v_cvt_pk_bf16_f32 v48, v38, v39
	v_add_co_u32_e32 v38, vcc, s67, v146
	s_nop 0
	v_lshl_add_u64 v[50:51], v[146:147], 0, s[34:35]
	v_addc_co_u32_e32 v39, vcc, 0, v147, vcc
	v_cvt_pk_bf16_f32 v49, v40, v41
	global_store_dwordx4 v[38:39], v[46:49], off
	v_cvt_pk_bf16_f32 v38, v42, v43
	v_cvt_pk_bf16_f32 v39, v44, v45
	v_cvt_pk_bf16_f32 v40, v34, v35
	v_cvt_pk_bf16_f32 v41, v36, v37
	global_store_dwordx4 v[50:51], v[38:41], off offset:256
	v_cvt_pk_bf16_f32 v30, v30, v31
	v_cvt_pk_bf16_f32 v31, v32, v33
	v_cvt_pk_bf16_f32 v32, v22, v23
	v_add_co_u32_e32 v22, vcc, s68, v146
	v_lshl_add_u64 v[34:35], v[146:147], 0, s[36:37]
	s_nop 0
	v_addc_co_u32_e32 v23, vcc, 0, v147, vcc
	v_cvt_pk_bf16_f32 v33, v24, v25
	global_store_dwordx4 v[22:23], v[30:33], off
	v_cvt_pk_bf16_f32 v22, v26, v27
	v_cvt_pk_bf16_f32 v23, v28, v29
	v_cvt_pk_bf16_f32 v24, v18, v19
	v_cvt_pk_bf16_f32 v25, v20, v21
	global_store_dwordx4 v[34:35], v[22:25], off offset:256
	v_cvt_pk_bf16_f32 v14, v14, v15
	v_cvt_pk_bf16_f32 v15, v16, v17
	v_cvt_pk_bf16_f32 v16, v6, v7
	v_add_co_u32_e32 v6, vcc, s69, v146
	v_lshl_add_u64 v[18:19], v[146:147], 0, s[38:39]
	s_nop 0
	v_addc_co_u32_e32 v7, vcc, 0, v147, vcc
	s_andn2_b64 vcc, exec, s[4:5]
	s_mov_b64 s[4:5], -1
	v_cvt_pk_bf16_f32 v17, v8, v9
	global_store_dwordx4 v[6:7], v[14:17], off
	v_cvt_pk_bf16_f32 v6, v10, v11
	v_cvt_pk_bf16_f32 v7, v12, v13
	v_cvt_pk_bf16_f32 v8, v2, v3
	v_cvt_pk_bf16_f32 v9, v4, v5
	global_store_dwordx4 v[18:19], v[6:9], off offset:256
	s_cbranch_vccnz .LBB0_1320
	s_andn2_b64 vcc, exec, s[8:9]
	s_cbranch_vccnz .LBB0_1319
	s_branch .LBB0_1319

.LBB0_1594:
	v_lshl_add_u32 v8, s54, 8, v1
	v_lshl_or_b32 v2, s73, 8, v187
	v_ashrrev_i32_e32 v9, 31, v8
	v_ashrrev_i32_e32 v3, 31, v2
	v_lshlrev_b64 v[4:5], 13, v[8:9]
	v_lshl_add_u64 v[4:5], s[12:13], 0, v[4:5]
	v_lshlrev_b64 v[10:11], 1, v[2:3]
	v_lshl_add_u64 v[2:3], v[4:5], 0, v[10:11]
	v_pk_mul_f32 v[4:5], v[158:159], s[36:37] op_sel_hi:[1,0]
	v_pk_mul_f32 v[6:7], v[160:161], s[36:37] op_sel_hi:[1,0]
	v_cvt_pk_bf16_f32 v4, v4, v5
	v_pk_mul_f32 v[12:13], v[156:157], s[36:37] op_sel_hi:[1,0]
	v_cvt_pk_bf16_f32 v5, v6, v7
	v_pk_mul_f32 v[14:15], v[154:155], s[36:37] op_sel_hi:[1,0]
	v_pk_mul_f32 v[16:17], v[138:139], s[36:37] op_sel_hi:[1,0]
	v_cvt_pk_bf16_f32 v6, v14, v15
	v_cvt_pk_bf16_f32 v7, v12, v13
	global_store_dwordx4 v[2:3], v[4:7], off
	v_pk_mul_f32 v[12:13], v[148:149], s[36:37] op_sel_hi:[1,0]
	v_pk_mul_f32 v[14:15], v[146:147], s[36:37] op_sel_hi:[1,0]
	v_pk_mul_f32 v[4:5], v[150:151], s[36:37] op_sel_hi:[1,0]
	v_pk_mul_f32 v[6:7], v[152:153], s[36:37] op_sel_hi:[1,0]
	v_cvt_pk_bf16_f32 v4, v4, v5
	s_nop 0
	v_cvt_pk_bf16_f32 v5, v6, v7
	v_cvt_pk_bf16_f32 v6, v14, v15
	v_cvt_pk_bf16_f32 v7, v12, v13
	global_store_dwordx4 v[2:3], v[4:7], off offset:256
	v_pk_mul_f32 v[14:15], v[140:141], s[36:37] op_sel_hi:[1,0]
	s_nop 0
	v_or_b32_e32 v4, 16, v8
	v_ashrrev_i32_e32 v5, 31, v4
	v_lshlrev_b64 v[4:5], 13, v[4:5]
	v_lshl_add_u64 v[4:5], s[12:13], 0, v[4:5]
	v_lshl_add_u64 v[12:13], v[4:5], 0, v[10:11]
	v_pk_mul_f32 v[4:5], v[142:143], s[36:37] op_sel_hi:[1,0]
	v_pk_mul_f32 v[6:7], v[144:145], s[36:37] op_sel_hi:[1,0]
	v_cvt_pk_bf16_f32 v4, v4, v5
	s_nop 0
	v_cvt_pk_bf16_f32 v5, v6, v7
	v_cvt_pk_bf16_f32 v6, v16, v17
	v_cvt_pk_bf16_f32 v7, v14, v15
	global_store_dwordx4 v[12:13], v[4:7], off
	v_pk_mul_f32 v[14:15], v[132:133], s[36:37] op_sel_hi:[1,0]
	v_pk_mul_f32 v[16:17], v[130:131], s[36:37] op_sel_hi:[1,0]
	v_pk_mul_f32 v[4:5], v[134:135], s[36:37] op_sel_hi:[1,0]
	v_pk_mul_f32 v[6:7], v[136:137], s[36:37] op_sel_hi:[1,0]
	v_cvt_pk_bf16_f32 v4, v4, v5
	s_nop 0
	v_cvt_pk_bf16_f32 v5, v6, v7
	v_cvt_pk_bf16_f32 v6, v16, v17
	v_cvt_pk_bf16_f32 v7, v14, v15
	global_store_dwordx4 v[12:13], v[4:7], off offset:256
	v_pk_mul_f32 v[14:15], v[120:121], s[36:37] op_sel_hi:[1,0]
	v_pk_mul_f32 v[16:17], v[118:119], s[36:37] op_sel_hi:[1,0]
	v_or_b32_e32 v4, 32, v8
	v_ashrrev_i32_e32 v5, 31, v4
	v_lshlrev_b64 v[4:5], 13, v[4:5]
	v_lshl_add_u64 v[4:5], s[12:13], 0, v[4:5]
	v_lshl_add_u64 v[12:13], v[4:5], 0, v[10:11]
	v_pk_mul_f32 v[4:5], v[126:127], s[36:37] op_sel_hi:[1,0]
	v_pk_mul_f32 v[6:7], v[128:129], s[36:37] op_sel_hi:[1,0]
	v_cvt_pk_bf16_f32 v4, v4, v5
	s_nop 0
	v_cvt_pk_bf16_f32 v5, v6, v7
	v_cvt_pk_bf16_f32 v6, v16, v17
	v_cvt_pk_bf16_f32 v7, v14, v15
	global_store_dwordx4 v[12:13], v[4:7], off
	v_pk_mul_f32 v[14:15], v[108:109], s[36:37] op_sel_hi:[1,0]
	v_pk_mul_f32 v[16:17], v[106:107], s[36:37] op_sel_hi:[1,0]
	v_pk_mul_f32 v[4:5], v[110:111], s[36:37] op_sel_hi:[1,0]
	v_pk_mul_f32 v[6:7], v[112:113], s[36:37] op_sel_hi:[1,0]
	v_cvt_pk_bf16_f32 v4, v4, v5
	s_nop 0
	v_cvt_pk_bf16_f32 v5, v6, v7
	v_cvt_pk_bf16_f32 v6, v16, v17
	v_cvt_pk_bf16_f32 v7, v14, v15
	global_store_dwordx4 v[12:13], v[4:7], off offset:256
	v_pk_mul_f32 v[12:13], v[82:83], s[36:37] op_sel_hi:[1,0]
	s_nop 0
	v_or_b32_e32 v4, 48, v8
	v_ashrrev_i32_e32 v5, 31, v4
	v_lshlrev_b64 v[4:5], 13, v[4:5]
	v_lshl_add_u64 v[4:5], s[12:13], 0, v[4:5]
	v_lshl_add_u64 v[8:9], v[4:5], 0, v[10:11]
	v_pk_mul_f32 v[6:7], v[92:93], s[36:37] op_sel_hi:[1,0]
	v_pk_mul_f32 v[4:5], v[90:91], s[36:37] op_sel_hi:[1,0]
	v_pk_mul_f32 v[10:11], v[84:85], s[36:37] op_sel_hi:[1,0]
	v_cvt_pk_bf16_f32 v4, v4, v5
	v_cvt_pk_bf16_f32 v5, v6, v7
	v_cvt_pk_bf16_f32 v6, v12, v13
	v_pk_mul_f32 v[12:13], v[74:75], s[36:37] op_sel_hi:[1,0]
	v_cvt_pk_bf16_f32 v7, v10, v11
	global_store_dwordx4 v[8:9], v[4:7], off
	v_pk_mul_f32 v[10:11], v[76:77], s[36:37] op_sel_hi:[1,0]
	s_nop 0
	v_pk_mul_f32 v[6:7], v[80:81], s[36:37] op_sel_hi:[1,0]
	v_pk_mul_f32 v[4:5], v[78:79], s[36:37] op_sel_hi:[1,0]
	s_nop 0
	v_cvt_pk_bf16_f32 v4, v4, v5
	v_cvt_pk_bf16_f32 v5, v6, v7
	v_cvt_pk_bf16_f32 v6, v12, v13
	v_cvt_pk_bf16_f32 v7, v10, v11
	global_store_dwordx4 v[8:9], v[4:7], off offset:256
	v_pk_mul_f32 v[10:11], v[116:117], s[36:37] op_sel_hi:[1,0]
	v_pk_mul_f32 v[12:13], v[114:115], s[36:37] op_sel_hi:[1,0]
	v_pk_mul_f32 v[6:7], v[124:125], s[36:37] op_sel_hi:[1,0]
	v_pk_mul_f32 v[4:5], v[122:123], s[36:37] op_sel_hi:[1,0]
	v_lshl_add_u64 v[8:9], v[2:3], 0, s[38:39]
	v_cvt_pk_bf16_f32 v4, v4, v5
	v_cvt_pk_bf16_f32 v5, v6, v7
	v_cvt_pk_bf16_f32 v6, v12, v13
	v_cvt_pk_bf16_f32 v7, v10, v11
	v_add_co_u32_e32 v10, vcc, s69, v2
	v_pk_mul_f32 v[12:13], v[98:99], s[36:37] op_sel_hi:[1,0]
	s_nop 0
	v_addc_co_u32_e32 v11, vcc, 0, v3, vcc
	global_store_dwordx4 v[10:11], v[4:7], off
	v_pk_mul_f32 v[10:11], v[100:101], s[36:37] op_sel_hi:[1,0]
	s_nop 0
	v_pk_mul_f32 v[6:7], v[104:105], s[36:37] op_sel_hi:[1,0]
	v_pk_mul_f32 v[4:5], v[102:103], s[36:37] op_sel_hi:[1,0]
	s_nop 0
	v_cvt_pk_bf16_f32 v4, v4, v5
	v_cvt_pk_bf16_f32 v5, v6, v7
	v_cvt_pk_bf16_f32 v6, v12, v13
	v_cvt_pk_bf16_f32 v7, v10, v11
	global_store_dwordx4 v[8:9], v[4:7], off offset:256
	v_pk_mul_f32 v[10:11], v[88:89], s[36:37] op_sel_hi:[1,0]
	v_pk_mul_f32 v[12:13], v[86:87], s[36:37] op_sel_hi:[1,0]
	v_pk_mul_f32 v[6:7], v[96:97], s[36:37] op_sel_hi:[1,0]
	v_pk_mul_f32 v[4:5], v[94:95], s[36:37] op_sel_hi:[1,0]
	v_lshl_add_u64 v[8:9], v[2:3], 0, s[40:41]
	v_cvt_pk_bf16_f32 v4, v4, v5
	v_cvt_pk_bf16_f32 v5, v6, v7
	v_cvt_pk_bf16_f32 v6, v12, v13
	v_cvt_pk_bf16_f32 v7, v10, v11
	v_add_co_u32_e32 v10, vcc, s70, v2
	v_pk_mul_f32 v[12:13], v[66:67], s[36:37] op_sel_hi:[1,0]
	s_nop 0
	v_addc_co_u32_e32 v11, vcc, 0, v3, vcc
	global_store_dwordx4 v[10:11], v[4:7], off
	v_pk_mul_f32 v[10:11], v[68:69], s[36:37] op_sel_hi:[1,0]
	s_nop 0
	v_pk_mul_f32 v[6:7], v[72:73], s[36:37] op_sel_hi:[1,0]
	v_pk_mul_f32 v[4:5], v[70:71], s[36:37] op_sel_hi:[1,0]
	s_nop 0
	v_cvt_pk_bf16_f32 v4, v4, v5
	v_cvt_pk_bf16_f32 v5, v6, v7
	v_cvt_pk_bf16_f32 v6, v12, v13
	v_cvt_pk_bf16_f32 v7, v10, v11
	global_store_dwordx4 v[8:9], v[4:7], off offset:256
	v_pk_mul_f32 v[10:11], v[60:61], s[36:37] op_sel_hi:[1,0]
	v_pk_mul_f32 v[12:13], v[58:59], s[36:37] op_sel_hi:[1,0]
	v_pk_mul_f32 v[6:7], v[64:65], s[36:37] op_sel_hi:[1,0]
	v_pk_mul_f32 v[4:5], v[62:63], s[36:37] op_sel_hi:[1,0]
	v_lshl_add_u64 v[8:9], v[2:3], 0, s[42:43]
	v_cvt_pk_bf16_f32 v4, v4, v5
	v_cvt_pk_bf16_f32 v5, v6, v7
	v_cvt_pk_bf16_f32 v6, v12, v13
	v_cvt_pk_bf16_f32 v7, v10, v11
	v_add_co_u32_e32 v10, vcc, s71, v2
	v_pk_mul_f32 v[12:13], v[50:51], s[36:37] op_sel_hi:[1,0]
	s_nop 0
	v_addc_co_u32_e32 v11, vcc, 0, v3, vcc
	global_store_dwordx4 v[10:11], v[4:7], off
	v_pk_mul_f32 v[10:11], v[52:53], s[36:37] op_sel_hi:[1,0]
	s_nop 0
	v_pk_mul_f32 v[4:5], v[54:55], s[36:37] op_sel_hi:[1,0]
	v_pk_mul_f32 v[6:7], v[56:57], s[36:37] op_sel_hi:[1,0]
	v_cvt_pk_bf16_f32 v4, v4, v5
	s_nop 0
	v_cvt_pk_bf16_f32 v5, v6, v7
	v_cvt_pk_bf16_f32 v6, v12, v13
	v_cvt_pk_bf16_f32 v7, v10, v11
	global_store_dwordx4 v[8:9], v[4:7], off offset:256
	v_lshl_add_u64 v[8:9], v[2:3], 0, s[44:45]
	v_add_co_u32_e32 v2, vcc, s72, v2
	v_pk_mul_f32 v[4:5], v[46:47], s[36:37] op_sel_hi:[1,0]
	v_pk_mul_f32 v[6:7], v[48:49], s[36:37] op_sel_hi:[1,0]
	v_cvt_pk_bf16_f32 v4, v4, v5
	v_addc_co_u32_e32 v3, vcc, 0, v3, vcc
	v_cvt_pk_bf16_f32 v5, v6, v7
	v_pk_mul_f32 v[10:11], v[44:45], s[36:37] op_sel_hi:[1,0]
	v_pk_mul_f32 v[12:13], v[42:43], s[36:37] op_sel_hi:[1,0]
	s_andn2_b64 vcc, exec, s[4:5]
	v_cvt_pk_bf16_f32 v6, v12, v13
	v_cvt_pk_bf16_f32 v7, v10, v11
	global_store_dwordx4 v[2:3], v[4:7], off
	v_pk_mul_f32 v[2:3], v[38:39], s[36:37] op_sel_hi:[1,0]
	s_mov_b64 s[4:5], -1
	v_pk_mul_f32 v[4:5], v[40:41], s[36:37] op_sel_hi:[1,0]
	v_pk_mul_f32 v[6:7], v[36:37], s[36:37] op_sel_hi:[1,0]
	v_pk_mul_f32 v[10:11], v[34:35], s[36:37] op_sel_hi:[1,0]
	v_cvt_pk_bf16_f32 v2, v2, v3
	v_cvt_pk_bf16_f32 v3, v4, v5
	s_nop 0
	v_cvt_pk_bf16_f32 v4, v10, v11
	v_cvt_pk_bf16_f32 v5, v6, v7
	global_store_dwordx4 v[8:9], v[2:5], off offset:256
	s_cbranch_vccnz .LBB0_1587
	s_andn2_b64 vcc, exec, s[6:7]
	s_cbranch_vccnz .LBB0_1586
	s_branch .LBB0_1586
